# v4 plus second-half residual loads of DN/pool/GLU epilogues hoisted
# speedup vs baseline: 1.0134x; 1.0134x over previous
;     __device__ __forceinline__ bool unit(int L, Unit& u) const { u.g = L; return order_mn(L, T / 256, NGU / 256, u.pm, u.pn); }
;     __device__ __forceinline__ bool unit(int L, Unit& u) const { u.g = L; return order_mn(L, T / 256, D / 256, u.pm, u.pn); }
;     __device__ __forceinline__ bool unit(int L, Unit& u) const { u.g = 0; return order_mn(L, T / 256, 8, u.pm, u.pn); }
;     __device__ __forceinline__ bool unit(int L, Unit& u) const { if (L >= NG * 4) return false; u.g = L >> 2; u.pm = (L >> 1) & 1; u.pn = L & 1; return true; }
;     __device__ __forceinline__ bool unit(int L, Unit& u) const { if (L >= NG * 8) return false; u.g = L >> 3; u.pm = (L >> 2) & 1; u.pn = L & 3; return true; }
;     ...
;         const bool has_next = p.unit((ui + 1) * G + c, nxt);
;         const char* nA = has_next ? p.a0(nxt) : cA; const char* nB = has_next ? p.b0(nxt) : cB;
;         const char* nA2 = P::SEG ? (has_next ? p.a1(nxt) : cA2) : nA; const char* nB2 = P::SEG ? (has_next ? p.b1(nxt) : cB2) : nB;
.LBB0_357:
	ds_read_b128 v[134:137], v190
	ds_read_b128 v[138:141], v190 offset:1024
	ds_read_b128 v[142:145], v190 offset:2048
	ds_read_b128 v[146:149], v190 offset:3072
	s_mov_b32 m0, s54
	v_lshl_add_u64 v[150:151], v[128:129], 0, s[34:35]
	ds_read_b128 v[166:169], v191
	ds_read_b128 v[170:173], v191 offset:1024
	ds_read_b128 v[174:177], v191 offset:2048
	ds_read_b128 v[178:181], v191 offset:3072
	ds_read_b128 v[194:197], v191 offset:4096
	ds_read_b128 v[198:201], v191 offset:5120
	ds_read_b128 v[202:205], v191 offset:6144
	ds_read_b128 v[206:209], v191 offset:7168
	global_load_lds_dwordx4 v[150:151], off
	s_mov_b32 m0, s55
	v_lshl_add_u64 v[150:151], v[130:131], 0, s[34:35]
	global_load_lds_dwordx4 v[150:151], off
	s_waitcnt lgkmcnt(8)
	s_barrier
	s_waitcnt lgkmcnt(0)
	s_setprio 1
	v_mfma_f32_16x16x32_bf16 v[116:119], v[134:137], v[166:169], v[116:119]
	s_add_i32 s36, s34, 0xfff50080
	v_mfma_f32_16x16x32_bf16 v[112:115], v[142:145], v[166:169], v[112:115]
	s_cmp_eq_u32 s67, 40
	v_mfma_f32_16x16x32_bf16 v[108:111], v[134:137], v[174:177], v[108:111]
	s_cselect_b32 s69, s27, s29
	v_mfma_f32_16x16x32_bf16 v[104:107], v[142:145], v[174:177], v[104:107]
	s_cselect_b32 s68, s26, s28
	v_mfma_f32_16x16x32_bf16 v[92:95], v[134:137], v[194:197], v[92:95]
	s_cselect_b32 s37, s9, s31
	v_mfma_f32_16x16x32_bf16 v[88:91], v[142:145], v[194:197], v[88:91]
	s_cselect_b32 s70, s8, s30
	v_mfma_f32_16x16x32_bf16 v[76:79], v[134:137], v[202:205], v[76:79]
	v_mfma_f32_16x16x32_bf16 v[72:75], v[142:145], v[202:205], v[72:75]
	v_mfma_f32_16x16x32_bf16 v[116:119], v[138:141], v[170:173], v[116:119]
	v_mfma_f32_16x16x32_bf16 v[112:115], v[146:149], v[170:173], v[112:115]
	v_mfma_f32_16x16x32_bf16 v[108:111], v[138:141], v[178:181], v[108:111]
	v_mfma_f32_16x16x32_bf16 v[104:107], v[146:149], v[178:181], v[104:107]
	v_mfma_f32_16x16x32_bf16 v[92:95], v[138:141], v[198:201], v[92:95]
	v_mfma_f32_16x16x32_bf16 v[88:91], v[146:149], v[198:201], v[88:91]
	v_mfma_f32_16x16x32_bf16 v[76:79], v[138:141], v[206:209], v[76:79]
	v_mfma_f32_16x16x32_bf16 v[72:75], v[146:149], v[206:209], v[72:75]
	s_setprio 0
	s_barrier
	s_cselect_b32 s71, 0, s36
	s_add_u32 s36, s70, s71
	s_addc_u32 s37, s37, 0
	s_mov_b32 m0, s56
	v_lshl_add_u64 v[150:151], s[36:37], 0, v[156:157]
	ds_read_b128 v[210:213], v192
	ds_read_b128 v[214:217], v192 offset:1024
	ds_read_b128 v[222:225], v192 offset:2048
	ds_read_b128 v[226:229], v192 offset:3072
	global_load_lds_dwordx4 v[150:151], off
	s_mov_b32 m0, s57
	v_lshl_add_u64 v[182:183], s[36:37], 0, v[160:161]
	global_load_lds_dwordx4 v[182:183], off
	s_barrier
	s_waitcnt lgkmcnt(0)
	s_setprio 1
	v_mfma_f32_16x16x32_bf16 v[124:127], v[210:213], v[166:169], v[124:127]
	v_mfma_f32_16x16x32_bf16 v[120:123], v[222:225], v[166:169], v[120:123]
	v_mfma_f32_16x16x32_bf16 v[100:103], v[210:213], v[174:177], v[100:103]
	v_mfma_f32_16x16x32_bf16 v[96:99], v[222:225], v[174:177], v[96:99]
	v_mfma_f32_16x16x32_bf16 v[84:87], v[210:213], v[194:197], v[84:87]
	v_mfma_f32_16x16x32_bf16 v[80:83], v[222:225], v[194:197], v[80:83]
	v_mfma_f32_16x16x32_bf16 v[68:71], v[210:213], v[202:205], v[68:71]
	v_mfma_f32_16x16x32_bf16 v[64:67], v[222:225], v[202:205], v[64:67]
	v_mfma_f32_16x16x32_bf16 v[124:127], v[214:217], v[170:173], v[124:127]
	v_mfma_f32_16x16x32_bf16 v[120:123], v[226:229], v[170:173], v[120:123]
	v_mfma_f32_16x16x32_bf16 v[100:103], v[214:217], v[178:181], v[100:103]
	v_mfma_f32_16x16x32_bf16 v[96:99], v[226:229], v[178:181], v[96:99]
	v_mfma_f32_16x16x32_bf16 v[84:87], v[214:217], v[198:201], v[84:87]
	v_mfma_f32_16x16x32_bf16 v[80:83], v[226:229], v[198:201], v[80:83]
	v_mfma_f32_16x16x32_bf16 v[68:71], v[214:217], v[206:209], v[68:71]
	v_mfma_f32_16x16x32_bf16 v[64:67], v[226:229], v[206:209], v[64:67]
	s_setprio 0
	s_add_u32 s68, s68, s71
	s_addc_u32 s69, s69, 0
	s_mov_b32 m0, s46
	v_lshl_add_u64 v[218:219], s[68:69], 0, v[154:155]
	s_barrier
	ds_read_b128 v[166:169], v191 offset:16384
	ds_read_b128 v[170:173], v191 offset:17408
	ds_read_b128 v[174:177], v191 offset:18432
	ds_read_b128 v[178:181], v191 offset:19456
	ds_read_b128 v[194:197], v191 offset:20480
	ds_read_b128 v[198:201], v191 offset:21504
	ds_read_b128 v[202:205], v191 offset:22528
	ds_read_b128 v[206:209], v191 offset:23552
	global_load_lds_dwordx4 v[218:219], off
	s_mov_b32 m0, s47
	v_lshl_add_u64 v[230:231], s[68:69], 0, v[158:159]
	global_load_lds_dwordx4 v[230:231], off
	s_barrier
	s_waitcnt lgkmcnt(0)
	s_setprio 1
	v_mfma_f32_16x16x32_bf16 v[52:55], v[134:137], v[166:169], v[52:55]
	v_mfma_f32_16x16x32_bf16 v[48:51], v[142:145], v[166:169], v[48:51]
	v_mfma_f32_16x16x32_bf16 v[44:47], v[134:137], v[174:177], v[44:47]
	v_mfma_f32_16x16x32_bf16 v[36:39], v[142:145], v[174:177], v[36:39]
	v_mfma_f32_16x16x32_bf16 v[28:31], v[134:137], v[194:197], v[28:31]
	v_mfma_f32_16x16x32_bf16 v[20:23], v[142:145], v[194:197], v[20:23]
	v_mfma_f32_16x16x32_bf16 v[12:15], v[134:137], v[202:205], v[12:15]
	v_mfma_f32_16x16x32_bf16 v[4:7], v[142:145], v[202:205], v[4:7]
	v_mfma_f32_16x16x32_bf16 v[52:55], v[138:141], v[170:173], v[52:55]
	v_mfma_f32_16x16x32_bf16 v[48:51], v[146:149], v[170:173], v[48:51]
	v_mfma_f32_16x16x32_bf16 v[44:47], v[138:141], v[178:181], v[44:47]
	v_mfma_f32_16x16x32_bf16 v[36:39], v[146:149], v[178:181], v[36:39]
	v_mfma_f32_16x16x32_bf16 v[28:31], v[138:141], v[198:201], v[28:31]
	v_mfma_f32_16x16x32_bf16 v[20:23], v[146:149], v[198:201], v[20:23]
	v_mfma_f32_16x16x32_bf16 v[12:15], v[138:141], v[206:209], v[12:15]
	v_mfma_f32_16x16x32_bf16 v[4:7], v[146:149], v[206:209], v[4:7]
	s_setprio 0
	s_barrier
	s_add_u32 s70, s36, 0xb0000
	s_addc_u32 s71, s37, 0
	s_mov_b32 m0, s0
	v_lshl_add_u64 v[134:135], s[70:71], 0, v[156:157]
	global_load_lds_dwordx4 v[134:135], off
	s_mov_b32 m0, s62
	v_lshl_add_u64 v[134:135], s[70:71], 0, v[160:161]
	global_load_lds_dwordx4 v[134:135], off
	s_waitcnt vmcnt(6)
	s_barrier
	s_setprio 1
	v_mfma_f32_16x16x32_bf16 v[60:63], v[210:213], v[166:169], v[60:63]
	v_mfma_f32_16x16x32_bf16 v[56:59], v[222:225], v[166:169], v[56:59]
	v_mfma_f32_16x16x32_bf16 v[40:43], v[210:213], v[174:177], v[40:43]
	v_mfma_f32_16x16x32_bf16 v[32:35], v[222:225], v[174:177], v[32:35]
	v_mfma_f32_16x16x32_bf16 v[24:27], v[210:213], v[194:197], v[24:27]
	v_mfma_f32_16x16x32_bf16 v[16:19], v[222:225], v[194:197], v[16:19]
	v_mfma_f32_16x16x32_bf16 v[8:11], v[210:213], v[202:205], v[8:11]
	v_mfma_f32_16x16x32_bf16 v[0:3], v[222:225], v[202:205], v[0:3]
	v_mfma_f32_16x16x32_bf16 v[60:63], v[214:217], v[170:173], v[60:63]
	v_mfma_f32_16x16x32_bf16 v[56:59], v[226:229], v[170:173], v[56:59]
	v_mfma_f32_16x16x32_bf16 v[40:43], v[214:217], v[178:181], v[40:43]
	v_mfma_f32_16x16x32_bf16 v[32:35], v[226:229], v[178:181], v[32:35]
	v_mfma_f32_16x16x32_bf16 v[24:27], v[214:217], v[198:201], v[24:27]
	v_mfma_f32_16x16x32_bf16 v[16:19], v[226:229], v[198:201], v[16:19]
	v_mfma_f32_16x16x32_bf16 v[8:11], v[214:217], v[206:209], v[8:11]
	v_mfma_f32_16x16x32_bf16 v[0:3], v[226:229], v[206:209], v[0:3]
	s_setprio 0
	s_barrier
	ds_read_b128 v[134:137], v132
	ds_read_b128 v[138:141], v132 offset:1024
	ds_read_b128 v[142:145], v132 offset:2048
	ds_read_b128 v[146:149], v132 offset:3072
	s_add_u32 s68, s68, 0xb0000
	s_addc_u32 s69, s69, 0
	s_mov_b32 m0, s48
	v_lshl_add_u64 v[210:211], s[68:69], 0, v[154:155]
	ds_read_b128 v[166:169], v191 offset:32768
	ds_read_b128 v[170:173], v191 offset:33792
	ds_read_b128 v[174:177], v191 offset:34816
	ds_read_b128 v[178:181], v191 offset:35840
	ds_read_b128 v[194:197], v191 offset:36864
	ds_read_b128 v[198:201], v191 offset:37888
	ds_read_b128 v[202:205], v191 offset:38912
	ds_read_b128 v[206:209], v191 offset:39936
	global_load_lds_dwordx4 v[210:211], off
	s_mov_b32 m0, s49
	v_lshl_add_u64 v[210:211], s[68:69], 0, v[158:159]
	global_load_lds_dwordx4 v[210:211], off
	s_waitcnt lgkmcnt(8)
	s_barrier
	s_waitcnt lgkmcnt(0)
	s_setprio 1
	v_mfma_f32_16x16x32_bf16 v[116:119], v[134:137], v[166:169], v[116:119]
	v_mfma_f32_16x16x32_bf16 v[112:115], v[142:145], v[166:169], v[112:115]
	v_mfma_f32_16x16x32_bf16 v[108:111], v[134:137], v[174:177], v[108:111]
	v_mfma_f32_16x16x32_bf16 v[104:107], v[142:145], v[174:177], v[104:107]
	v_mfma_f32_16x16x32_bf16 v[92:95], v[134:137], v[194:197], v[92:95]
	v_mfma_f32_16x16x32_bf16 v[88:91], v[142:145], v[194:197], v[88:91]
	v_mfma_f32_16x16x32_bf16 v[76:79], v[134:137], v[202:205], v[76:79]
	v_mfma_f32_16x16x32_bf16 v[72:75], v[142:145], v[202:205], v[72:75]
	v_mfma_f32_16x16x32_bf16 v[116:119], v[138:141], v[170:173], v[116:119]
	v_mfma_f32_16x16x32_bf16 v[112:115], v[146:149], v[170:173], v[112:115]
	v_mfma_f32_16x16x32_bf16 v[108:111], v[138:141], v[178:181], v[108:111]
	v_mfma_f32_16x16x32_bf16 v[104:107], v[146:149], v[178:181], v[104:107]
	v_mfma_f32_16x16x32_bf16 v[92:95], v[138:141], v[198:201], v[92:95]
	v_mfma_f32_16x16x32_bf16 v[88:91], v[146:149], v[198:201], v[88:91]
	v_mfma_f32_16x16x32_bf16 v[76:79], v[138:141], v[206:209], v[76:79]
	v_mfma_f32_16x16x32_bf16 v[72:75], v[146:149], v[206:209], v[72:75]
	s_setprio 0
	s_barrier
	s_mov_b32 m0, s63
	v_lshl_add_u64 v[150:151], v[150:151], 0, s[10:11]
	ds_read_b128 v[210:213], v133
	ds_read_b128 v[214:217], v133 offset:1024
	ds_read_b128 v[222:225], v133 offset:2048
	ds_read_b128 v[226:229], v133 offset:3072
	global_load_lds_dwordx4 v[150:151], off
	s_mov_b32 m0, s64
	v_lshl_add_u64 v[150:151], v[182:183], 0, s[10:11]
	global_load_lds_dwordx4 v[150:151], off
	s_barrier
	s_waitcnt lgkmcnt(0)
	s_setprio 1
	v_mfma_f32_16x16x32_bf16 v[124:127], v[210:213], v[166:169], v[124:127]
	v_mfma_f32_16x16x32_bf16 v[120:123], v[222:225], v[166:169], v[120:123]
	v_mfma_f32_16x16x32_bf16 v[100:103], v[210:213], v[174:177], v[100:103]
	v_mfma_f32_16x16x32_bf16 v[96:99], v[222:225], v[174:177], v[96:99]
	v_mfma_f32_16x16x32_bf16 v[84:87], v[210:213], v[194:197], v[84:87]
	v_mfma_f32_16x16x32_bf16 v[80:83], v[222:225], v[194:197], v[80:83]
	v_mfma_f32_16x16x32_bf16 v[68:71], v[210:213], v[202:205], v[68:71]
	v_mfma_f32_16x16x32_bf16 v[64:67], v[222:225], v[202:205], v[64:67]
	v_mfma_f32_16x16x32_bf16 v[124:127], v[214:217], v[170:173], v[124:127]
	v_mfma_f32_16x16x32_bf16 v[120:123], v[226:229], v[170:173], v[120:123]
	v_mfma_f32_16x16x32_bf16 v[100:103], v[214:217], v[178:181], v[100:103]
	v_mfma_f32_16x16x32_bf16 v[96:99], v[226:229], v[178:181], v[96:99]
	v_mfma_f32_16x16x32_bf16 v[84:87], v[214:217], v[198:201], v[84:87]
	v_mfma_f32_16x16x32_bf16 v[80:83], v[226:229], v[198:201], v[80:83]
	v_mfma_f32_16x16x32_bf16 v[68:71], v[214:217], v[206:209], v[68:71]
	v_mfma_f32_16x16x32_bf16 v[64:67], v[226:229], v[206:209], v[64:67]
	s_setprio 0
	s_mov_b32 m0, s51
	v_lshl_add_u64 v[150:151], v[218:219], 0, s[10:11]
	s_barrier
	ds_read_b128 v[166:169], v191 offset:49152
	ds_read_b128 v[170:173], v191 offset:50176
	ds_read_b128 v[174:177], v191 offset:51200
	ds_read_b128 v[178:181], v191 offset:52224
	ds_read_b128 v[194:197], v191 offset:53248
	ds_read_b128 v[198:201], v191 offset:54272
	ds_read_b128 v[202:205], v191 offset:55296
	ds_read_b128 v[206:209], v191 offset:56320
	global_load_lds_dwordx4 v[150:151], off
	s_mov_b32 m0, s52
	v_lshl_add_u64 v[150:151], v[230:231], 0, s[10:11]
	global_load_lds_dwordx4 v[150:151], off
	s_barrier
;     ...
;         G_PAIR(0, 1);
; #pragma unroll 1
;         for (int t = 2; t < nt; t += 2) G_PAIR(t, 0);
	s_waitcnt lgkmcnt(0)
	s_setprio 1
	v_mfma_f32_16x16x32_bf16 v[52:55], v[134:137], v[166:169], v[52:55]
	v_mfma_f32_16x16x32_bf16 v[48:51], v[142:145], v[166:169], v[48:51]
	v_mfma_f32_16x16x32_bf16 v[44:47], v[134:137], v[174:177], v[44:47]
	v_mfma_f32_16x16x32_bf16 v[36:39], v[142:145], v[174:177], v[36:39]
	v_mfma_f32_16x16x32_bf16 v[28:31], v[134:137], v[194:197], v[28:31]
	v_mfma_f32_16x16x32_bf16 v[20:23], v[142:145], v[194:197], v[20:23]
	v_mfma_f32_16x16x32_bf16 v[12:15], v[134:137], v[202:205], v[12:15]
	v_mfma_f32_16x16x32_bf16 v[4:7], v[142:145], v[202:205], v[4:7]
	v_mfma_f32_16x16x32_bf16 v[52:55], v[138:141], v[170:173], v[52:55]
	v_mfma_f32_16x16x32_bf16 v[48:51], v[146:149], v[170:173], v[48:51]
	v_mfma_f32_16x16x32_bf16 v[44:47], v[138:141], v[178:181], v[44:47]
	v_mfma_f32_16x16x32_bf16 v[36:39], v[146:149], v[178:181], v[36:39]
	v_mfma_f32_16x16x32_bf16 v[28:31], v[138:141], v[198:201], v[28:31]
	v_mfma_f32_16x16x32_bf16 v[20:23], v[146:149], v[198:201], v[20:23]
	v_mfma_f32_16x16x32_bf16 v[12:15], v[138:141], v[206:209], v[12:15]
	v_mfma_f32_16x16x32_bf16 v[4:7], v[146:149], v[206:209], v[4:7]
	s_setprio 0
	s_barrier
	s_add_u32 s36, s36, 0xb0080
	s_addc_u32 s37, s37, 0
	s_mov_b32 m0, s65
	v_lshl_add_u64 v[134:135], s[36:37], 0, v[156:157]
	global_load_lds_dwordx4 v[134:135], off
	s_mov_b32 m0, s66
	v_lshl_add_u64 v[134:135], s[36:37], 0, v[160:161]
	global_load_lds_dwordx4 v[134:135], off
	s_waitcnt vmcnt(6)
	s_barrier
	s_setprio 1
	v_mfma_f32_16x16x32_bf16 v[60:63], v[210:213], v[166:169], v[60:63]
	v_mfma_f32_16x16x32_bf16 v[56:59], v[222:225], v[166:169], v[56:59]
	v_mfma_f32_16x16x32_bf16 v[40:43], v[210:213], v[174:177], v[40:43]
	v_mfma_f32_16x16x32_bf16 v[32:35], v[222:225], v[174:177], v[32:35]
	v_mfma_f32_16x16x32_bf16 v[24:27], v[210:213], v[194:197], v[24:27]
	v_mfma_f32_16x16x32_bf16 v[16:19], v[222:225], v[194:197], v[16:19]
	v_mfma_f32_16x16x32_bf16 v[8:11], v[210:213], v[202:205], v[8:11]
	v_mfma_f32_16x16x32_bf16 v[0:3], v[222:225], v[202:205], v[0:3]
	v_mfma_f32_16x16x32_bf16 v[60:63], v[214:217], v[170:173], v[60:63]
	v_mfma_f32_16x16x32_bf16 v[56:59], v[226:229], v[170:173], v[56:59]
	v_mfma_f32_16x16x32_bf16 v[40:43], v[214:217], v[178:181], v[40:43]
	v_mfma_f32_16x16x32_bf16 v[32:35], v[226:229], v[178:181], v[32:35]
	v_mfma_f32_16x16x32_bf16 v[24:27], v[214:217], v[198:201], v[24:27]
	v_mfma_f32_16x16x32_bf16 v[16:19], v[226:229], v[198:201], v[16:19]
	v_mfma_f32_16x16x32_bf16 v[8:11], v[214:217], v[206:209], v[8:11]
	v_mfma_f32_16x16x32_bf16 v[0:3], v[226:229], v[206:209], v[0:3]
	s_setprio 0
	s_add_i32 s67, s67, 2
	s_add_u32 s34, s34, 0x100
	s_addc_u32 s35, s35, 0
	s_cmp_gt_u32 s67, 41
	s_barrier
	s_cbranch_scc0 .LBB0_357
; __device__ __forceinline__ unsigned pk2(float lo, float hi) { unsigned r; asm volatile("v_cvt_pk_bf16_f32 %0, %1, %2" : "=v"(r) : "v"(lo), "v"(hi)); return r; }
; __device__ __forceinline__ unsigned pk2(float lo, float hi) { return f2bf(lo) | (f2bf(hi) << 16); }
;     __device__ __forceinline__ void epi(const f32x4 (&acc)[2][2][4][2], const Unit& u, int wr, int wc, int fr, int fq) const {
;     ...
;         const int row0 = u.pm * 256 + wr * 64 + fr, col0 = u.pn * 256 + wc * 32 + 8 * fq;
; #pragma unroll
;         for (int ai = 0; ai < 2; ++ai) {
;             u32x4 xo[4][2];
; #pragma unroll
;             for (int m = 0; m < 4; ++m)
; #pragma unroll
;                 for (int bj = 0; bj < 2; ++bj) xo[m][bj] = *(const u32x4*)(xb + (size_t)(row0 + ai * 128 + m * 16) * D + col0 + bj * 128);
; #pragma unroll
;             for (int m = 0; m < 4; ++m) {
;                 const int row = row0 + ai * 128 + m * 16; const size_t off = (size_t)row * D + col0; float ss = 0.f;
; #pragma unroll
;                 for (int bj = 0; bj < 2; ++bj) {
;                     const u32x4 o = xo[m][bj]; const f32x4 a0v = acc[ai][bj][m][0], a1v = acc[ai][bj][m][1];
;                     const float v0 = bf_lo(o.x) + coef * a0v[0], v1 = bf_hi(o.x) + coef * a0v[1], v2 = bf_lo(o.y) + coef * a0v[2], v3 = bf_hi(o.y) + coef * a0v[3];
;                     const float v4 = bf_lo(o.z) + coef * a1v[0], v5 = bf_hi(o.z) + coef * a1v[1], v6 = bf_lo(o.w) + coef * a1v[2], v7 = bf_hi(o.w) + coef * a1v[3];
;                     u32x4 w; w.x = pk2(v0, v1); w.y = pk2(v2, v3); w.z = pk2(v4, v5); w.w = pk2(v6, v7);
;                     *(u32x4*)(xb + off + bj * 128) = w;
;                     ss += ((v0 * v0 + v1 * v1) + (v2 * v2 + v3 * v3)) + ((v4 * v4 + v5 * v5) + (v6 * v6 + v7 * v7));
;                 }
;                 ss += __shfl_xor(ss, 16); ss += __shfl_xor(ss, 32);
;                 if (fq == 0) rowss[(size_t)row * 32 + u.pn * 4 + wc] = ss;
	v_lshl_or_b32 v166, s40, 8, v189
	v_lshl_add_u32 v170, s61, 8, v153
	v_ashrrev_i32_e32 v167, 31, v166
	v_lshlrev_b64 v[202:203], 1, v[166:167]
	v_ashrrev_i32_e32 v171, 31, v170
	v_lshl_add_u64 v[168:169], s[20:21], 0, v[202:203]
	v_lshlrev_b64 v[204:205], 11, v[170:171]
	v_lshl_add_u64 v[128:129], v[168:169], 0, v[204:205]
	v_mov_b32_e32 v218, 0x40000
	v_mov_b32_e32 v219, 0
	v_lshl_add_u64 v[216:217], v[128:129], 0, v[218:219]
	v_mov_b32_e32 v218, 0x8000
	global_load_dwordx4 v[194:197], v[128:129], off
	global_load_dwordx4 v[198:201], v[128:129], off offset:256
	v_or_b32_e32 v180, 16, v170
	v_or_b32_e32 v176, 32, v170
	v_or_b32_e32 v172, 48, v170
	v_ashrrev_i32_e32 v181, 31, v180
	v_ashrrev_i32_e32 v177, 31, v176
	v_ashrrev_i32_e32 v173, 31, v172
	v_lshlrev_b64 v[182:183], 11, v[180:181]
	v_lshlrev_b64 v[178:179], 11, v[176:177]
	v_lshlrev_b64 v[174:175], 11, v[172:173]
	v_lshl_add_u64 v[128:129], v[168:169], 0, v[182:183]
	v_lshl_add_u64 v[130:131], v[168:169], 0, v[178:179]
	v_lshl_add_u64 v[206:207], v[168:169], 0, v[174:175]
	global_load_dwordx4 v[148:151], v[128:129], off
	global_load_dwordx4 v[144:147], v[128:129], off offset:256
	global_load_dwordx4 v[140:143], v[130:131], off
	global_load_dwordx4 v[136:139], v[130:131], off offset:256
	global_load_dwordx4 v[132:135], v[206:207], off
	s_nop 0
	global_load_dwordx4 v[128:131], v[206:207], off offset:256
	global_load_dwordx4 v[222:225], v[216:217], off
	global_load_dwordx4 v[226:229], v[216:217], off offset:256
	v_lshl_add_u64 v[216:217], v[216:217], 0, v[218:219]
	global_load_dwordx4 v[230:233], v[216:217], off
	global_load_dwordx4 v[234:237], v[216:217], off offset:256
	v_lshl_add_u64 v[216:217], v[216:217], 0, v[218:219]
	global_load_dwordx4 v[238:241], v[216:217], off
	global_load_dwordx4 v[242:245], v[216:217], off offset:256
	v_lshl_add_u64 v[216:217], v[216:217], 0, v[218:219]
	global_load_dwordx4 v[246:249], v[216:217], off
	global_load_dwordx4 v[250:253], v[216:217], off offset:256
	v_and_b32_e32 v206, 64, v193
	v_xor_b32_e32 v208, 16, v193
	v_add_u32_e32 v206, 64, v206
	v_cmp_lt_i32_e32 vcc, v208, v206
	s_waitcnt vmcnt(8)
	v_lshlrev_b32_e32 v209, 16, v195
	v_cndmask_b32_e32 v207, v193, v208, vcc
	v_lshlrev_b32_e32 v208, 16, v194
	v_and_b32_e32 v194, 0xffff0000, v194
	v_and_b32_e32 v195, 0xffff0000, v195
	v_lshlrev_b32_e32 v210, 16, v196
	v_and_b32_e32 v196, 0xffff0000, v196
	v_lshlrev_b32_e32 v211, 16, v197
	v_and_b32_e32 v197, 0xffff0000, v197
	v_lshlrev_b32_e32 v212, 16, v198
	v_and_b32_e32 v198, 0xffff0000, v198
	v_lshlrev_b32_e32 v213, 16, v199
	v_and_b32_e32 v199, 0xffff0000, v199
	v_lshlrev_b32_e32 v214, 16, v200
	v_and_b32_e32 v200, 0xffff0000, v200
	v_lshlrev_b32_e32 v215, 16, v201
	v_and_b32_e32 v201, 0xffff0000, v201
	v_fmac_f32_e32 v194, 0.5, v117
	v_fmac_f32_e32 v195, 0.5, v119
	v_fmac_f32_e32 v196, 0.5, v113
	v_fmac_f32_e32 v197, 0.5, v115
	v_fmac_f32_e32 v198, 0.5, v125
	v_fmac_f32_e32 v199, 0.5, v127
	v_fmac_f32_e32 v200, 0.5, v121
	v_fmac_f32_e32 v201, 0.5, v123
	v_fmac_f32_e32 v208, 0.5, v116
	v_fmac_f32_e32 v209, 0.5, v118
	v_fmac_f32_e32 v210, 0.5, v112
	v_fmac_f32_e32 v211, 0.5, v114
	v_fmac_f32_e32 v212, 0.5, v124
	v_fmac_f32_e32 v213, 0.5, v126
	v_fmac_f32_e32 v214, 0.5, v120
	v_fmac_f32_e32 v215, 0.5, v122
	v_mul_f32_e32 v112, v194, v194
	v_mul_f32_e32 v113, v195, v195
	v_mul_f32_e32 v118, v196, v196
	v_mul_f32_e32 v119, v197, v197
	v_mul_f32_e32 v120, v198, v198
	v_mul_f32_e32 v121, v199, v199
	v_mul_f32_e32 v122, v200, v200
	v_mul_f32_e32 v123, v201, v201
	v_fmac_f32_e32 v112, v208, v208
	v_fmac_f32_e32 v113, v209, v209
	v_fmac_f32_e32 v118, v210, v210
	v_fmac_f32_e32 v119, v211, v211
	v_fmac_f32_e32 v120, v212, v212
	v_fmac_f32_e32 v121, v213, v213
	v_fmac_f32_e32 v122, v214, v214
	v_fmac_f32_e32 v123, v215, v215
	v_add_f32_e32 v112, v112, v113
	v_add_f32_e32 v113, v118, v119
	v_add_f32_e32 v118, v120, v121
	v_add_f32_e32 v119, v122, v123
	v_add_f32_e32 v112, v112, v113
	v_add_f32_e32 v113, v118, v119
	v_add_f32_e32 v113, v112, v113
	v_lshlrev_b32_e32 v112, 2, v207
	ds_bpermute_b32 v122, v112, v113
	v_lshl_add_u64 v[118:119], s[20:21], 0, v[204:205]
	v_cvt_pk_bf16_f32 v114, v208, v194
	v_lshl_add_u64 v[120:121], v[118:119], 0, v[202:203]
	v_cvt_pk_bf16_f32 v115, v209, v195
	v_cvt_pk_bf16_f32 v116, v210, v196
	v_cvt_pk_bf16_f32 v117, v211, v197
	global_store_dwordx4 v[120:121], v[114:117], off
	s_waitcnt lgkmcnt(0)
	s_nop 0
	v_add_f32_e32 v114, v113, v122
	v_xor_b32_e32 v113, 32, v193
	v_cmp_lt_i32_e32 vcc, v113, v206
	v_cvt_pk_bf16_f32 v116, v212, v198
	v_cvt_pk_bf16_f32 v117, v213, v199
	v_cvt_pk_bf16_f32 v118, v214, v200
	v_cvt_pk_bf16_f32 v119, v215, v201
	global_store_dwordx4 v[120:121], v[116:119], off offset:256
	s_nop 0
	v_cndmask_b32_e32 v113, v193, v113, vcc
	v_lshlrev_b32_e32 v113, 2, v113
	ds_bpermute_b32 v115, v113, v114
	s_and_saveexec_b64 s[28:29], s[6:7]
	s_cbranch_execz .LBB0_360
	s_waitcnt lgkmcnt(0)
	v_add_f32_e32 v116, v114, v115
	s_lshl_b32 s30, s40, 2
	v_lshlrev_b64 v[114:115], 7, v[170:171]
	s_ashr_i32 s31, s30, 31
	v_lshl_add_u64 v[114:115], s[2:3], 0, v[114:115]
	v_lshl_add_u64 v[114:115], s[30:31], 2, v[114:115]
	s_lshl_b32 s0, s50, 2
	v_lshl_add_u64 v[114:115], v[114:115], 0, s[0:1]
	global_store_dword v[114:115], v116, off

.LBB0_920:
	ds_read_b128 v[132:135], v172
	ds_read_b128 v[136:139], v172 offset:1024
	ds_read_b128 v[152:155], v172 offset:2048
	ds_read_b128 v[156:159], v172 offset:3072
	s_mov_b32 m0, s48
	v_lshl_add_u64 v[168:169], v[120:121], 0, s[30:31]
	ds_read_b128 v[160:163], v173
	ds_read_b128 v[164:167], v173 offset:1024
	ds_read_b128 v[178:181], v173 offset:2048
	ds_read_b128 v[182:185], v173 offset:3072
	ds_read_b128 v[186:189], v173 offset:4096
	ds_read_b128 v[190:193], v173 offset:5120
	ds_read_b128 v[194:197], v173 offset:6144
	ds_read_b128 v[198:201], v173 offset:7168
	global_load_lds_dwordx4 v[168:169], off
	s_mov_b32 m0, s49
	v_lshl_add_u64 v[168:169], v[122:123], 0, s[30:31]
	global_load_lds_dwordx4 v[168:169], off
	s_waitcnt lgkmcnt(8)
	s_barrier
	s_waitcnt lgkmcnt(0)
	s_setprio 1
	v_mfma_f32_16x16x32_bf16 v[116:119], v[132:135], v[160:163], v[116:119]
	s_add_i32 s19, s30, 0xfffc0080
	v_mfma_f32_16x16x32_bf16 v[112:115], v[152:155], v[160:163], v[112:115]
	s_cmp_eq_u32 s17, 12
	v_mfma_f32_16x16x32_bf16 v[100:103], v[132:135], v[178:181], v[100:103]
	s_cselect_b64 s[34:35], -1, 0
	v_mfma_f32_16x16x32_bf16 v[96:99], v[152:155], v[178:181], v[96:99]
	s_and_b64 s[60:61], s[34:35], exec
	v_mfma_f32_16x16x32_bf16 v[84:87], v[132:135], v[186:189], v[84:87]
	s_cselect_b32 s19, 0, s19
	v_mfma_f32_16x16x32_bf16 v[80:83], v[152:155], v[186:189], v[80:83]
	s_and_b64 s[34:35], s[28:29], s[34:35]
	v_mfma_f32_16x16x32_bf16 v[68:71], v[132:135], v[194:197], v[68:71]
	s_and_b64 s[34:35], s[34:35], exec
	v_mfma_f32_16x16x32_bf16 v[64:67], v[152:155], v[194:197], v[64:67]
	s_cselect_b32 s61, s21, s25
	v_mfma_f32_16x16x32_bf16 v[116:119], v[136:139], v[164:167], v[116:119]
	s_cselect_b32 s60, s20, s24
	v_mfma_f32_16x16x32_bf16 v[112:115], v[156:159], v[164:167], v[112:115]
	s_cselect_b32 s35, s23, s27
	v_mfma_f32_16x16x32_bf16 v[100:103], v[136:139], v[182:185], v[100:103]
	s_cselect_b32 s34, s22, s26
	v_mfma_f32_16x16x32_bf16 v[96:99], v[156:159], v[182:185], v[96:99]
	v_mfma_f32_16x16x32_bf16 v[84:87], v[136:139], v[190:193], v[84:87]
	v_mfma_f32_16x16x32_bf16 v[80:83], v[156:159], v[190:193], v[80:83]
	v_mfma_f32_16x16x32_bf16 v[68:71], v[136:139], v[198:201], v[68:71]
	v_mfma_f32_16x16x32_bf16 v[64:67], v[156:159], v[198:201], v[64:67]
	s_setprio 0
	s_barrier
	s_add_u32 s34, s34, s19
	s_addc_u32 s35, s35, 0
	s_mov_b32 m0, s50
	v_lshl_add_u64 v[168:169], s[34:35], 0, v[144:145]
	ds_read_b128 v[202:205], v174
	ds_read_b128 v[206:209], v174 offset:1024
	ds_read_b128 v[210:213], v174 offset:2048
	ds_read_b128 v[214:217], v174 offset:3072
	global_load_lds_dwordx4 v[168:169], off
	s_mov_b32 m0, s51
	v_lshl_add_u64 v[218:219], s[34:35], 0, v[140:141]
	global_load_lds_dwordx4 v[218:219], off
	s_barrier
	s_waitcnt lgkmcnt(0)
	s_setprio 1
	v_mfma_f32_16x16x32_bf16 v[128:131], v[202:205], v[160:163], v[128:131]
	v_mfma_f32_16x16x32_bf16 v[124:127], v[210:213], v[160:163], v[124:127]
	v_mfma_f32_16x16x32_bf16 v[108:111], v[202:205], v[178:181], v[108:111]
	v_mfma_f32_16x16x32_bf16 v[104:107], v[210:213], v[178:181], v[104:107]
	v_mfma_f32_16x16x32_bf16 v[92:95], v[202:205], v[186:189], v[92:95]
	v_mfma_f32_16x16x32_bf16 v[88:91], v[210:213], v[186:189], v[88:91]
	v_mfma_f32_16x16x32_bf16 v[76:79], v[202:205], v[194:197], v[76:79]
	v_mfma_f32_16x16x32_bf16 v[72:75], v[210:213], v[194:197], v[72:75]
	v_mfma_f32_16x16x32_bf16 v[128:131], v[206:209], v[164:167], v[128:131]
	v_mfma_f32_16x16x32_bf16 v[124:127], v[214:217], v[164:167], v[124:127]
	v_mfma_f32_16x16x32_bf16 v[108:111], v[206:209], v[182:185], v[108:111]
	v_mfma_f32_16x16x32_bf16 v[104:107], v[214:217], v[182:185], v[104:107]
	v_mfma_f32_16x16x32_bf16 v[92:95], v[206:209], v[190:193], v[92:95]
	v_mfma_f32_16x16x32_bf16 v[88:91], v[214:217], v[190:193], v[88:91]
	v_mfma_f32_16x16x32_bf16 v[76:79], v[206:209], v[198:201], v[76:79]
	v_mfma_f32_16x16x32_bf16 v[72:75], v[214:217], v[198:201], v[72:75]
	s_setprio 0
	s_add_u32 s60, s60, s19
	s_addc_u32 s61, s61, 0
	s_mov_b32 m0, s41
	v_lshl_add_u64 v[222:223], s[60:61], 0, v[146:147]
	s_barrier
	ds_read_b128 v[160:163], v173 offset:16384
	ds_read_b128 v[164:167], v173 offset:17408
	ds_read_b128 v[178:181], v173 offset:18432
	ds_read_b128 v[182:185], v173 offset:19456
	ds_read_b128 v[186:189], v173 offset:20480
	ds_read_b128 v[190:193], v173 offset:21504
	ds_read_b128 v[194:197], v173 offset:22528
	ds_read_b128 v[198:201], v173 offset:23552
	global_load_lds_dwordx4 v[222:223], off
	s_mov_b32 m0, s42
	v_lshl_add_u64 v[224:225], s[60:61], 0, v[142:143]
	global_load_lds_dwordx4 v[224:225], off
	s_barrier
	s_waitcnt lgkmcnt(0)
	s_setprio 1
	v_mfma_f32_16x16x32_bf16 v[52:55], v[132:135], v[160:163], v[52:55]
	v_mfma_f32_16x16x32_bf16 v[48:51], v[152:155], v[160:163], v[48:51]
	v_mfma_f32_16x16x32_bf16 v[36:39], v[132:135], v[178:181], v[36:39]
	v_mfma_f32_16x16x32_bf16 v[32:35], v[152:155], v[178:181], v[32:35]
	v_mfma_f32_16x16x32_bf16 v[20:23], v[132:135], v[186:189], v[20:23]
	v_mfma_f32_16x16x32_bf16 v[16:19], v[152:155], v[186:189], v[16:19]
	v_mfma_f32_16x16x32_bf16 v[4:7], v[132:135], v[194:197], v[4:7]
	v_mfma_f32_16x16x32_bf16 v[0:3], v[152:155], v[194:197], v[0:3]
	v_mfma_f32_16x16x32_bf16 v[52:55], v[136:139], v[164:167], v[52:55]
	v_mfma_f32_16x16x32_bf16 v[48:51], v[156:159], v[164:167], v[48:51]
	v_mfma_f32_16x16x32_bf16 v[36:39], v[136:139], v[182:185], v[36:39]
	v_mfma_f32_16x16x32_bf16 v[32:35], v[156:159], v[182:185], v[32:35]
	v_mfma_f32_16x16x32_bf16 v[20:23], v[136:139], v[190:193], v[20:23]
	v_mfma_f32_16x16x32_bf16 v[16:19], v[156:159], v[190:193], v[16:19]
	v_mfma_f32_16x16x32_bf16 v[4:7], v[136:139], v[198:201], v[4:7]
	v_mfma_f32_16x16x32_bf16 v[0:3], v[156:159], v[198:201], v[0:3]
	s_setprio 0
	s_barrier
	s_add_u32 s62, s34, 0x40000
	s_addc_u32 s63, s35, 0
	s_mov_b32 m0, s52
	v_lshl_add_u64 v[132:133], s[62:63], 0, v[144:145]
	global_load_lds_dwordx4 v[132:133], off
	s_mov_b32 m0, s53
	v_lshl_add_u64 v[132:133], s[62:63], 0, v[140:141]
	global_load_lds_dwordx4 v[132:133], off
	s_waitcnt vmcnt(6)
	s_barrier
	s_setprio 1
	v_mfma_f32_16x16x32_bf16 v[60:63], v[202:205], v[160:163], v[60:63]
	v_mfma_f32_16x16x32_bf16 v[56:59], v[210:213], v[160:163], v[56:59]
	v_mfma_f32_16x16x32_bf16 v[44:47], v[202:205], v[178:181], v[44:47]
	v_mfma_f32_16x16x32_bf16 v[40:43], v[210:213], v[178:181], v[40:43]
	v_mfma_f32_16x16x32_bf16 v[28:31], v[202:205], v[186:189], v[28:31]
	v_mfma_f32_16x16x32_bf16 v[24:27], v[210:213], v[186:189], v[24:27]
	v_mfma_f32_16x16x32_bf16 v[12:15], v[202:205], v[194:197], v[12:15]
	v_mfma_f32_16x16x32_bf16 v[8:11], v[210:213], v[194:197], v[8:11]
	v_mfma_f32_16x16x32_bf16 v[60:63], v[206:209], v[164:167], v[60:63]
	v_mfma_f32_16x16x32_bf16 v[56:59], v[214:217], v[164:167], v[56:59]
	v_mfma_f32_16x16x32_bf16 v[44:47], v[206:209], v[182:185], v[44:47]
	v_mfma_f32_16x16x32_bf16 v[40:43], v[214:217], v[182:185], v[40:43]
	v_mfma_f32_16x16x32_bf16 v[28:31], v[206:209], v[190:193], v[28:31]
	v_mfma_f32_16x16x32_bf16 v[24:27], v[214:217], v[190:193], v[24:27]
	v_mfma_f32_16x16x32_bf16 v[12:15], v[206:209], v[198:201], v[12:15]
	v_mfma_f32_16x16x32_bf16 v[8:11], v[214:217], v[198:201], v[8:11]
	s_setprio 0
	s_barrier
	ds_read_b128 v[132:135], v176
	ds_read_b128 v[136:139], v176 offset:1024
	ds_read_b128 v[152:155], v176 offset:2048
	ds_read_b128 v[156:159], v176 offset:3072
	s_add_u32 s60, s60, 0x40000
	s_addc_u32 s61, s61, 0
	s_mov_b32 m0, s43
	v_lshl_add_u64 v[202:203], s[60:61], 0, v[146:147]
	ds_read_b128 v[160:163], v173 offset:32768
	ds_read_b128 v[164:167], v173 offset:33792
	ds_read_b128 v[178:181], v173 offset:34816
	ds_read_b128 v[182:185], v173 offset:35840
	ds_read_b128 v[186:189], v173 offset:36864
	ds_read_b128 v[190:193], v173 offset:37888
	ds_read_b128 v[194:197], v173 offset:38912
	ds_read_b128 v[198:201], v173 offset:39936
	global_load_lds_dwordx4 v[202:203], off
	s_mov_b32 m0, s44
	v_lshl_add_u64 v[202:203], s[60:61], 0, v[142:143]
	global_load_lds_dwordx4 v[202:203], off
	s_waitcnt lgkmcnt(8)
	s_barrier
	s_waitcnt lgkmcnt(0)
	s_setprio 1
	v_mfma_f32_16x16x32_bf16 v[116:119], v[132:135], v[160:163], v[116:119]
	v_mfma_f32_16x16x32_bf16 v[112:115], v[152:155], v[160:163], v[112:115]
	v_mfma_f32_16x16x32_bf16 v[100:103], v[132:135], v[178:181], v[100:103]
	v_mfma_f32_16x16x32_bf16 v[96:99], v[152:155], v[178:181], v[96:99]
	v_mfma_f32_16x16x32_bf16 v[84:87], v[132:135], v[186:189], v[84:87]
	v_mfma_f32_16x16x32_bf16 v[80:83], v[152:155], v[186:189], v[80:83]
	v_mfma_f32_16x16x32_bf16 v[68:71], v[132:135], v[194:197], v[68:71]
	v_mfma_f32_16x16x32_bf16 v[64:67], v[152:155], v[194:197], v[64:67]
	v_mfma_f32_16x16x32_bf16 v[116:119], v[136:139], v[164:167], v[116:119]
	v_mfma_f32_16x16x32_bf16 v[112:115], v[156:159], v[164:167], v[112:115]
	v_mfma_f32_16x16x32_bf16 v[100:103], v[136:139], v[182:185], v[100:103]
	v_mfma_f32_16x16x32_bf16 v[96:99], v[156:159], v[182:185], v[96:99]
	v_mfma_f32_16x16x32_bf16 v[84:87], v[136:139], v[190:193], v[84:87]
	v_mfma_f32_16x16x32_bf16 v[80:83], v[156:159], v[190:193], v[80:83]
	v_mfma_f32_16x16x32_bf16 v[68:71], v[136:139], v[198:201], v[68:71]
	v_mfma_f32_16x16x32_bf16 v[64:67], v[156:159], v[198:201], v[64:67]
	s_setprio 0
	s_barrier
	s_mov_b32 m0, s54
	v_lshl_add_u64 v[168:169], v[168:169], 0, s[6:7]
	ds_read_b128 v[202:205], v177
	ds_read_b128 v[206:209], v177 offset:1024
	ds_read_b128 v[210:213], v177 offset:2048
	ds_read_b128 v[214:217], v177 offset:3072
	global_load_lds_dwordx4 v[168:169], off
	s_mov_b32 m0, s55
	v_lshl_add_u64 v[168:169], v[218:219], 0, s[6:7]
	global_load_lds_dwordx4 v[168:169], off
	s_barrier
	s_waitcnt lgkmcnt(0)
	s_setprio 1
	v_mfma_f32_16x16x32_bf16 v[128:131], v[202:205], v[160:163], v[128:131]
	v_mfma_f32_16x16x32_bf16 v[124:127], v[210:213], v[160:163], v[124:127]
	v_mfma_f32_16x16x32_bf16 v[108:111], v[202:205], v[178:181], v[108:111]
	v_mfma_f32_16x16x32_bf16 v[104:107], v[210:213], v[178:181], v[104:107]
	v_mfma_f32_16x16x32_bf16 v[92:95], v[202:205], v[186:189], v[92:95]
	v_mfma_f32_16x16x32_bf16 v[88:91], v[210:213], v[186:189], v[88:91]
	v_mfma_f32_16x16x32_bf16 v[76:79], v[202:205], v[194:197], v[76:79]
	v_mfma_f32_16x16x32_bf16 v[72:75], v[210:213], v[194:197], v[72:75]
	v_mfma_f32_16x16x32_bf16 v[128:131], v[206:209], v[164:167], v[128:131]
	v_mfma_f32_16x16x32_bf16 v[124:127], v[214:217], v[164:167], v[124:127]
	v_mfma_f32_16x16x32_bf16 v[108:111], v[206:209], v[182:185], v[108:111]
	v_mfma_f32_16x16x32_bf16 v[104:107], v[214:217], v[182:185], v[104:107]
	v_mfma_f32_16x16x32_bf16 v[92:95], v[206:209], v[190:193], v[92:95]
	v_mfma_f32_16x16x32_bf16 v[88:91], v[214:217], v[190:193], v[88:91]
	v_mfma_f32_16x16x32_bf16 v[76:79], v[206:209], v[198:201], v[76:79]
	v_mfma_f32_16x16x32_bf16 v[72:75], v[214:217], v[198:201], v[72:75]
	s_setprio 0
	s_mov_b32 m0, s46
	v_lshl_add_u64 v[168:169], v[222:223], 0, s[6:7]
	s_barrier
	ds_read_b128 v[160:163], v173 offset:49152
	ds_read_b128 v[164:167], v173 offset:50176
	ds_read_b128 v[178:181], v173 offset:51200
	ds_read_b128 v[182:185], v173 offset:52224
	ds_read_b128 v[186:189], v173 offset:53248
	ds_read_b128 v[190:193], v173 offset:54272
	ds_read_b128 v[194:197], v173 offset:55296
	ds_read_b128 v[198:201], v173 offset:56320
	global_load_lds_dwordx4 v[168:169], off
	s_mov_b32 m0, s47
	v_lshl_add_u64 v[168:169], v[224:225], 0, s[6:7]
	global_load_lds_dwordx4 v[168:169], off
	s_barrier
;     ...
;         G_PAIR(0, 1);
; #pragma unroll 1
;         for (int t = 2; t < nt; t += 2) G_PAIR(t, 0);
	s_waitcnt lgkmcnt(0)
	s_setprio 1
	v_mfma_f32_16x16x32_bf16 v[52:55], v[132:135], v[160:163], v[52:55]
	v_mfma_f32_16x16x32_bf16 v[48:51], v[152:155], v[160:163], v[48:51]
	v_mfma_f32_16x16x32_bf16 v[36:39], v[132:135], v[178:181], v[36:39]
	v_mfma_f32_16x16x32_bf16 v[32:35], v[152:155], v[178:181], v[32:35]
	v_mfma_f32_16x16x32_bf16 v[20:23], v[132:135], v[186:189], v[20:23]
	v_mfma_f32_16x16x32_bf16 v[16:19], v[152:155], v[186:189], v[16:19]
	v_mfma_f32_16x16x32_bf16 v[4:7], v[132:135], v[194:197], v[4:7]
	v_mfma_f32_16x16x32_bf16 v[0:3], v[152:155], v[194:197], v[0:3]
	v_mfma_f32_16x16x32_bf16 v[52:55], v[136:139], v[164:167], v[52:55]
	v_mfma_f32_16x16x32_bf16 v[48:51], v[156:159], v[164:167], v[48:51]
	v_mfma_f32_16x16x32_bf16 v[36:39], v[136:139], v[182:185], v[36:39]
	v_mfma_f32_16x16x32_bf16 v[32:35], v[156:159], v[182:185], v[32:35]
	v_mfma_f32_16x16x32_bf16 v[20:23], v[136:139], v[190:193], v[20:23]
	v_mfma_f32_16x16x32_bf16 v[16:19], v[156:159], v[190:193], v[16:19]
	v_mfma_f32_16x16x32_bf16 v[4:7], v[136:139], v[198:201], v[4:7]
	v_mfma_f32_16x16x32_bf16 v[0:3], v[156:159], v[198:201], v[0:3]
	s_setprio 0
	s_barrier
	s_add_u32 s34, s34, 0x40080
	s_addc_u32 s35, s35, 0
	s_mov_b32 m0, s56
	v_lshl_add_u64 v[132:133], s[34:35], 0, v[144:145]
	global_load_lds_dwordx4 v[132:133], off
	s_mov_b32 m0, s57
	v_lshl_add_u64 v[132:133], s[34:35], 0, v[140:141]
	global_load_lds_dwordx4 v[132:133], off
	s_waitcnt vmcnt(6)
	s_barrier
	s_setprio 1
	v_mfma_f32_16x16x32_bf16 v[60:63], v[202:205], v[160:163], v[60:63]
	v_mfma_f32_16x16x32_bf16 v[56:59], v[210:213], v[160:163], v[56:59]
	v_mfma_f32_16x16x32_bf16 v[44:47], v[202:205], v[178:181], v[44:47]
	v_mfma_f32_16x16x32_bf16 v[40:43], v[210:213], v[178:181], v[40:43]
	v_mfma_f32_16x16x32_bf16 v[28:31], v[202:205], v[186:189], v[28:31]
	v_mfma_f32_16x16x32_bf16 v[24:27], v[210:213], v[186:189], v[24:27]
	v_mfma_f32_16x16x32_bf16 v[12:15], v[202:205], v[194:197], v[12:15]
	v_mfma_f32_16x16x32_bf16 v[8:11], v[210:213], v[194:197], v[8:11]
	v_mfma_f32_16x16x32_bf16 v[60:63], v[206:209], v[164:167], v[60:63]
	v_mfma_f32_16x16x32_bf16 v[56:59], v[214:217], v[164:167], v[56:59]
	v_mfma_f32_16x16x32_bf16 v[44:47], v[206:209], v[182:185], v[44:47]
	v_mfma_f32_16x16x32_bf16 v[40:43], v[214:217], v[182:185], v[40:43]
	v_mfma_f32_16x16x32_bf16 v[28:31], v[206:209], v[190:193], v[28:31]
	v_mfma_f32_16x16x32_bf16 v[24:27], v[214:217], v[190:193], v[24:27]
	v_mfma_f32_16x16x32_bf16 v[12:15], v[206:209], v[198:201], v[12:15]
	v_mfma_f32_16x16x32_bf16 v[8:11], v[214:217], v[198:201], v[8:11]
	s_setprio 0
	s_add_i32 s17, s17, 2
	s_add_u32 s30, s30, 0x100
	s_addc_u32 s31, s31, 0
	s_cmp_gt_u32 s17, 13
	s_barrier
	s_cbranch_scc0 .LBB0_920
; __device__ __forceinline__ unsigned pk2(float lo, float hi) { unsigned r; asm volatile("v_cvt_pk_bf16_f32 %0, %1, %2" : "=v"(r) : "v"(lo), "v"(hi)); return r; }
; __device__ __forceinline__ unsigned pk2(float lo, float hi) { return f2bf(lo) | (f2bf(hi) << 16); }
; __device__ __forceinline__ float fast_sigmoid(float z) { return __builtin_amdgcn_rcpf(1.0f + __expf(-z)); }
;     __device__ __forceinline__ void epi(const f32x4 (&acc)[2][2][4][2], const Unit& u, int wr, int wc, int fr, int fq) const {
;         const int row0 = u.pm * 256 + wr * 64 + fr, col0 = u.pn * 128 + wc * 32 + 8 * fq;
; #pragma unroll
;         for (int ai = 0; ai < 2; ++ai) {
;             u32x4 xo[4];
; #pragma unroll
;             for (int m = 0; m < 4; ++m) xo[m] = *(const u32x4*)(xb + (size_t)(row0 + ai * 128 + m * 16) * D + col0);
; #pragma unroll
;             for (int m = 0; m < 4; ++m) {
;                 const int row = row0 + ai * 128 + m * 16; const size_t off = (size_t)row * D + col0;
;                 const u32x4 o = xo[m]; const f32x4 a0v = acc[ai][0][m][0], a1v = acc[ai][0][m][1], b0v = acc[ai][1][m][0], b1v = acc[ai][1][m][1];
;                 const float v0 = bf_lo(o.x) + coef * a0v[0] * fast_sigmoid(b0v[0]), v1 = bf_hi(o.x) + coef * a0v[1] * fast_sigmoid(b0v[1]);
;                 const float v2 = bf_lo(o.y) + coef * a0v[2] * fast_sigmoid(b0v[2]), v3 = bf_hi(o.y) + coef * a0v[3] * fast_sigmoid(b0v[3]);
;                 const float v4 = bf_lo(o.z) + coef * a1v[0] * fast_sigmoid(b1v[0]), v5 = bf_hi(o.z) + coef * a1v[1] * fast_sigmoid(b1v[1]);
;                 const float v6 = bf_lo(o.w) + coef * a1v[2] * fast_sigmoid(b1v[2]), v7 = bf_hi(o.w) + coef * a1v[3] * fast_sigmoid(b1v[3]);
;                 u32x4 w; w.x = pk2(v0, v1); w.y = pk2(v2, v3); w.z = pk2(v4, v5); w.w = pk2(v6, v7);
;                 *(u32x4*)(xb + off) = w;
;                 float ss = ((v0 * v0 + v1 * v1) + (v2 * v2 + v3 * v3)) + ((v4 * v4 + v5 * v5) + (v6 * v6 + v7 * v7));
;                 ss += __shfl_xor(ss, 16); ss += __shfl_xor(ss, 32);
;                 if (fq == 0) rowss[(size_t)row * 32 + u.pn * 4 + wc] = ss;
	v_lshl_or_b32 v152, s59, 7, v171
	v_lshl_add_u32 v156, s8, 8, v170
	v_ashrrev_i32_e32 v153, 31, v152
	v_lshlrev_b64 v[182:183], 1, v[152:153]
	v_ashrrev_i32_e32 v157, 31, v156
	v_lshl_add_u64 v[154:155], s[0:1], 0, v[182:183]
	v_lshlrev_b64 v[184:185], 11, v[156:157]
	v_lshl_add_u64 v[120:121], v[154:155], 0, v[184:185]
	v_mov_b32_e32 v236, 0x40000
	v_mov_b32_e32 v237, 0
	v_lshl_add_u64 v[234:235], v[120:121], 0, v[236:237]
	v_mov_b32_e32 v236, 0x8000
	global_load_dwordx4 v[178:181], v[120:121], off
	v_or_b32_e32 v166, 16, v156
	v_or_b32_e32 v162, 32, v156
	v_or_b32_e32 v158, 48, v156
	v_ashrrev_i32_e32 v167, 31, v166
	v_ashrrev_i32_e32 v163, 31, v162
	v_ashrrev_i32_e32 v159, 31, v158
	v_lshlrev_b64 v[168:169], 11, v[166:167]
	v_lshlrev_b64 v[164:165], 11, v[162:163]
	v_lshlrev_b64 v[160:161], 11, v[158:159]
	v_lshl_add_u64 v[120:121], v[154:155], 0, v[168:169]
	v_lshl_add_u64 v[122:123], v[154:155], 0, v[164:165]
	v_lshl_add_u64 v[186:187], v[154:155], 0, v[160:161]
	global_load_dwordx4 v[136:139], v[120:121], off
	global_load_dwordx4 v[132:135], v[122:123], off
	s_nop 0
	global_load_dwordx4 v[120:123], v[186:187], off
	global_load_dwordx4 v[238:241], v[234:235], off
	v_lshl_add_u64 v[234:235], v[234:235], 0, v[236:237]
	global_load_dwordx4 v[242:245], v[234:235], off
	v_lshl_add_u64 v[234:235], v[234:235], 0, v[236:237]
	global_load_dwordx4 v[246:249], v[234:235], off
	v_lshl_add_u64 v[234:235], v[234:235], 0, v[236:237]
	global_load_dwordx4 v[250:253], v[234:235], off
	v_mul_f32_e32 v129, 0xbfb8aa3b, v129
	v_mul_f32_e32 v131, 0xbfb8aa3b, v131
	v_mul_f32_e32 v125, 0xbfb8aa3b, v125
	v_mul_f32_e32 v127, 0xbfb8aa3b, v127
	v_mul_f32_e32 v128, 0xbfb8aa3b, v128
	v_mul_f32_e32 v130, 0xbfb8aa3b, v130
	v_mul_f32_e32 v124, 0xbfb8aa3b, v124
	v_mul_f32_e32 v126, 0xbfb8aa3b, v126
	v_exp_f32_e32 v129, v129
	v_exp_f32_e32 v131, v131
	v_exp_f32_e32 v125, v125
	v_exp_f32_e32 v127, v127
	v_exp_f32_e32 v128, v128
	v_exp_f32_e32 v130, v130
	v_exp_f32_e32 v189, v124
	v_exp_f32_e32 v126, v126
	v_and_b32_e32 v187, 64, v175
	v_xor_b32_e32 v186, 16, v175
	v_add_u32_e32 v187, 64, v187
	v_cmp_lt_i32_e32 vcc, v186, v187
	v_add_f32_e32 v129, 1.0, v129
	v_add_f32_e32 v131, 1.0, v131
	v_add_f32_e32 v125, 1.0, v125
	v_add_f32_e32 v127, 1.0, v127
	v_cndmask_b32_e32 v124, v175, v186, vcc
	v_add_f32_e32 v128, 1.0, v128
	v_add_f32_e32 v130, 1.0, v130
	v_add_f32_e32 v186, 1.0, v189
	v_add_f32_e32 v126, 1.0, v126
	v_rcp_f32_e32 v129, v129
	v_rcp_f32_e32 v131, v131
	v_rcp_f32_e32 v125, v125
	v_rcp_f32_e32 v127, v127
	v_rcp_f32_e32 v128, v128
	v_rcp_f32_e32 v130, v130
	v_rcp_f32_e32 v186, v186
	v_rcp_f32_e32 v126, v126
	v_lshlrev_b32_e32 v124, 2, v124
	v_xor_b32_e32 v188, 32, v175
	v_cmp_lt_i32_e32 vcc, v188, v187
	s_lshl_b32 s24, s59, 2
	s_ashr_i32 s25, s24, 31
	s_waitcnt vmcnt(4)
	v_lshlrev_b32_e32 v189, 16, v178
	v_and_b32_e32 v178, 0xffff0000, v178
	v_lshlrev_b32_e32 v190, 16, v179
	v_and_b32_e32 v179, 0xffff0000, v179
	v_lshlrev_b32_e32 v191, 16, v180
	v_and_b32_e32 v180, 0xffff0000, v180
	v_lshlrev_b32_e32 v192, 16, v181
	v_and_b32_e32 v181, 0xffff0000, v181
	v_fmac_f32_e32 v178, v117, v129
	v_fmac_f32_e32 v179, v119, v131
	v_fmac_f32_e32 v180, v113, v125
	v_fmac_f32_e32 v181, v115, v127
	v_fmac_f32_e32 v189, v116, v128
	v_fmac_f32_e32 v190, v118, v130
	v_fmac_f32_e32 v191, v112, v186
	v_fmac_f32_e32 v192, v114, v126
	v_mul_f32_e32 v112, v178, v178
	v_mul_f32_e32 v113, v179, v179
	v_mul_f32_e32 v114, v180, v180
	v_mul_f32_e32 v115, v181, v181
	v_fmac_f32_e32 v112, v189, v189
	v_fmac_f32_e32 v113, v190, v190
	v_fmac_f32_e32 v114, v191, v191
	v_fmac_f32_e32 v115, v192, v192
	v_add_f32_e32 v112, v112, v113
	v_add_f32_e32 v113, v114, v115
	v_add_f32_e32 v112, v112, v113
	ds_bpermute_b32 v113, v124, v112
	v_lshl_add_u64 v[126:127], s[0:1], 0, v[184:185]
	v_lshl_add_u64 v[126:127], v[126:127], 0, v[182:183]
	v_cvt_pk_bf16_f32 v116, v189, v178
	v_cvt_pk_bf16_f32 v117, v190, v179
	s_waitcnt lgkmcnt(0)
	v_add_f32_e32 v113, v112, v113
	v_cndmask_b32_e32 v112, v175, v188, vcc
	v_lshlrev_b32_e32 v112, 2, v112
	ds_bpermute_b32 v114, v112, v113
	v_cvt_pk_bf16_f32 v118, v191, v180
	v_cvt_pk_bf16_f32 v119, v192, v181
	global_store_dwordx4 v[126:127], v[116:119], off
	s_and_saveexec_b64 s[26:27], s[4:5]
	s_cbranch_execz .LBB0_923
	v_lshlrev_b64 v[116:117], 7, v[156:157]
	v_lshl_add_u64 v[116:117], s[2:3], 0, v[116:117]
	v_lshl_add_u64 v[116:117], s[24:25], 2, v[116:117]
	s_lshl_b32 s8, s45, 2
	v_lshl_add_u64 v[116:117], v[116:117], 0, s[8:9]
	s_waitcnt lgkmcnt(0)
	v_add_f32_e32 v113, v113, v114
	global_store_dword v[116:117], v113, off

;     __device__ __forceinline__ bool unit(int L, Unit& u) const { u.g = L; return order_mn(L, T / 256, NGU / 256, u.pm, u.pn); }
;     __device__ __forceinline__ bool unit(int L, Unit& u) const { u.g = L; return order_mn(L, T / 256, D / 256, u.pm, u.pn); }
;     __device__ __forceinline__ bool unit(int L, Unit& u) const { u.g = 0; return order_mn(L, T / 256, 8, u.pm, u.pn); }
;     __device__ __forceinline__ bool unit(int L, Unit& u) const { if (L >= NG * 4) return false; u.g = L >> 2; u.pm = (L >> 1) & 1; u.pn = L & 1; return true; }
;     __device__ __forceinline__ bool unit(int L, Unit& u) const { if (L >= NG * 8) return false; u.g = L >> 3; u.pm = (L >> 2) & 1; u.pn = L & 3; return true; }
;     ...
;         const bool has_next = p.unit((ui + 1) * G + c, nxt);
;         const char* nA = has_next ? p.a0(nxt) : cA; const char* nB = has_next ? p.b0(nxt) : cB;
;         const char* nA2 = P::SEG ? (has_next ? p.a1(nxt) : cA2) : nA; const char* nB2 = P::SEG ? (has_next ? p.b1(nxt) : cB2) : nB;
.LBB0_1670:
	s_waitcnt lgkmcnt(0)
	ds_read_b128 v[0:3], v173
	ds_read_b128 v[4:7], v173 offset:1024
	ds_read_b128 v[8:11], v173 offset:2048
	ds_read_b128 v[12:15], v173 offset:3072
	s_lshl_b64 s[22:23], s[16:17], 17
	s_add_u32 s22, s35, s22
	s_addc_u32 s23, s36, s23
	s_add_u32 s52, s24, 0x40080
	s_addc_u32 s53, s25, 0
	s_mov_b32 m0, s47
	v_lshl_add_u64 v[48:49], s[52:53], 0, v[150:151]
	ds_read_b128 v[16:19], v174
	ds_read_b128 v[20:23], v174 offset:1024
	ds_read_b128 v[24:27], v174 offset:2048
	ds_read_b128 v[28:31], v174 offset:3072
	ds_read_b128 v[32:35], v174 offset:4096
	ds_read_b128 v[36:39], v174 offset:5120
	ds_read_b128 v[40:43], v174 offset:6144
	ds_read_b128 v[44:47], v174 offset:7168
	global_load_lds_dwordx4 v[48:49], off
	s_mov_b32 m0, s48
	v_lshl_add_u64 v[48:49], s[52:53], 0, v[146:147]
	global_load_lds_dwordx4 v[48:49], off
	s_waitcnt lgkmcnt(8)
	s_barrier
	s_waitcnt lgkmcnt(0)
	s_setprio 1
	v_mfma_f32_16x16x32_bf16 v[48:51], v[0:3], v[16:19], 0
	v_mfma_f32_16x16x32_bf16 v[52:55], v[8:11], v[16:19], 0
	v_mfma_f32_16x16x32_bf16 v[56:59], v[0:3], v[24:27], 0
	v_mfma_f32_16x16x32_bf16 v[60:63], v[8:11], v[24:27], 0
	v_mfma_f32_16x16x32_bf16 v[64:67], v[0:3], v[32:35], 0
	v_mfma_f32_16x16x32_bf16 v[68:71], v[8:11], v[32:35], 0
	v_mfma_f32_16x16x32_bf16 v[72:75], v[0:3], v[40:43], 0
	v_mfma_f32_16x16x32_bf16 v[76:79], v[8:11], v[40:43], 0
	v_mfma_f32_16x16x32_bf16 v[48:51], v[4:7], v[20:23], v[48:51]
	v_mfma_f32_16x16x32_bf16 v[52:55], v[12:15], v[20:23], v[52:55]
	v_mfma_f32_16x16x32_bf16 v[56:59], v[4:7], v[28:31], v[56:59]
	v_mfma_f32_16x16x32_bf16 v[60:63], v[12:15], v[28:31], v[60:63]
	v_mfma_f32_16x16x32_bf16 v[64:67], v[4:7], v[36:39], v[64:67]
	v_mfma_f32_16x16x32_bf16 v[68:71], v[12:15], v[36:39], v[68:71]
	v_mfma_f32_16x16x32_bf16 v[72:75], v[4:7], v[44:47], v[72:75]
	v_mfma_f32_16x16x32_bf16 v[76:79], v[12:15], v[44:47], v[76:79]
	s_setprio 0
	s_barrier
	v_lshl_add_u64 v[168:169], s[26:27], 0, v[148:149]
	s_mov_b32 m0, s49
	v_lshl_add_u64 v[96:97], v[168:169], 0, s[10:11]
	v_lshl_add_u64 v[212:213], s[26:27], 0, v[144:145]
	ds_read_b128 v[80:83], v175
	ds_read_b128 v[84:87], v175 offset:1024
	ds_read_b128 v[88:91], v175 offset:2048
	ds_read_b128 v[92:95], v175 offset:3072
	global_load_lds_dwordx4 v[96:97], off
	s_mov_b32 m0, s50
	v_lshl_add_u64 v[96:97], v[212:213], 0, s[10:11]
	global_load_lds_dwordx4 v[96:97], off
	s_barrier
	s_waitcnt lgkmcnt(0)
	s_setprio 1
	v_mfma_f32_16x16x32_bf16 v[96:99], v[80:83], v[16:19], 0
	v_mfma_f32_16x16x32_bf16 v[16:19], v[88:91], v[16:19], 0
	v_mfma_f32_16x16x32_bf16 v[100:103], v[80:83], v[24:27], 0
	v_mfma_f32_16x16x32_bf16 v[24:27], v[88:91], v[24:27], 0
	v_mfma_f32_16x16x32_bf16 v[104:107], v[80:83], v[32:35], 0
	v_mfma_f32_16x16x32_bf16 v[32:35], v[88:91], v[32:35], 0
	v_mfma_f32_16x16x32_bf16 v[108:111], v[80:83], v[40:43], 0
	v_mfma_f32_16x16x32_bf16 v[40:43], v[88:91], v[40:43], 0
	v_mfma_f32_16x16x32_bf16 v[96:99], v[84:87], v[20:23], v[96:99]
	v_mfma_f32_16x16x32_bf16 v[16:19], v[92:95], v[20:23], v[16:19]
	v_mfma_f32_16x16x32_bf16 v[20:23], v[84:87], v[28:31], v[100:103]
	v_mfma_f32_16x16x32_bf16 v[24:27], v[92:95], v[28:31], v[24:27]
	v_mfma_f32_16x16x32_bf16 v[28:31], v[84:87], v[36:39], v[104:107]
	v_mfma_f32_16x16x32_bf16 v[32:35], v[92:95], v[36:39], v[32:35]
	v_mfma_f32_16x16x32_bf16 v[36:39], v[84:87], v[44:47], v[108:111]
	v_mfma_f32_16x16x32_bf16 v[40:43], v[92:95], v[44:47], v[40:43]
	s_setprio 0
	v_lshl_add_u64 v[214:215], s[24:25], 0, v[150:151]
	s_mov_b32 m0, s38
	v_lshl_add_u64 v[128:129], v[214:215], 0, s[10:11]
	v_lshl_add_u64 v[216:217], s[24:25], 0, v[146:147]
	s_barrier
	ds_read_b128 v[44:47], v174 offset:16384
	ds_read_b128 v[100:103], v174 offset:17408
	ds_read_b128 v[104:107], v174 offset:18432
	ds_read_b128 v[108:111], v174 offset:19456
	ds_read_b128 v[112:115], v174 offset:20480
	ds_read_b128 v[116:119], v174 offset:21504
	ds_read_b128 v[120:123], v174 offset:22528
	ds_read_b128 v[124:127], v174 offset:23552
	global_load_lds_dwordx4 v[128:129], off
	s_mov_b32 m0, s39
	v_lshl_add_u64 v[128:129], v[216:217], 0, s[10:11]
	global_load_lds_dwordx4 v[128:129], off
	s_barrier
	s_waitcnt lgkmcnt(0)
	s_setprio 1
	v_mfma_f32_16x16x32_bf16 v[128:131], v[0:3], v[44:47], 0
	v_mfma_f32_16x16x32_bf16 v[132:135], v[8:11], v[44:47], 0
	v_mfma_f32_16x16x32_bf16 v[136:139], v[0:3], v[104:107], 0
	v_mfma_f32_16x16x32_bf16 v[140:143], v[8:11], v[104:107], 0
	v_mfma_f32_16x16x32_bf16 v[152:155], v[0:3], v[112:115], 0
	v_mfma_f32_16x16x32_bf16 v[156:159], v[8:11], v[112:115], 0
	v_mfma_f32_16x16x32_bf16 v[0:3], v[0:3], v[120:123], 0
	v_mfma_f32_16x16x32_bf16 v[8:11], v[8:11], v[120:123], 0
	v_mfma_f32_16x16x32_bf16 v[128:131], v[4:7], v[100:103], v[128:131]
	v_mfma_f32_16x16x32_bf16 v[136:139], v[4:7], v[108:111], v[136:139]
	v_mfma_f32_16x16x32_bf16 v[140:143], v[12:15], v[108:111], v[140:143]
	v_mfma_f32_16x16x32_bf16 v[152:155], v[4:7], v[116:119], v[152:155]
	v_mfma_f32_16x16x32_bf16 v[156:159], v[12:15], v[116:119], v[156:159]
	v_mfma_f32_16x16x32_bf16 v[0:3], v[4:7], v[124:127], v[0:3]
	v_mfma_f32_16x16x32_bf16 v[4:7], v[12:15], v[124:127], v[8:11]
	v_mfma_f32_16x16x32_bf16 v[132:135], v[12:15], v[100:103], v[132:135]
	s_setprio 0
	s_barrier
	s_add_u32 s52, s26, 0x10100
	s_addc_u32 s53, s27, 0
	s_add_i32 s19, s46, s37
	v_lshl_add_u64 v[8:9], s[52:53], 0, v[148:149]
	s_mov_b32 m0, s19
	s_add_i32 s17, s19, 0x2000
	global_load_lds_dwordx4 v[8:9], off
	s_mov_b32 m0, s17
	v_lshl_add_u64 v[8:9], s[52:53], 0, v[144:145]
	global_load_lds_dwordx4 v[8:9], off
	s_waitcnt vmcnt(6)
	s_barrier
	s_setprio 1
	v_mfma_f32_16x16x32_bf16 v[8:11], v[80:83], v[44:47], 0
	v_mfma_f32_16x16x32_bf16 v[12:15], v[88:91], v[44:47], 0
	v_mfma_f32_16x16x32_bf16 v[44:47], v[80:83], v[104:107], 0
	v_mfma_f32_16x16x32_bf16 v[104:107], v[88:91], v[104:107], 0
	v_mfma_f32_16x16x32_bf16 v[160:163], v[80:83], v[112:115], 0
	v_mfma_f32_16x16x32_bf16 v[112:115], v[88:91], v[112:115], 0
	v_mfma_f32_16x16x32_bf16 v[80:83], v[80:83], v[120:123], 0
	v_mfma_f32_16x16x32_bf16 v[88:91], v[88:91], v[120:123], 0
	v_mfma_f32_16x16x32_bf16 v[8:11], v[84:87], v[100:103], v[8:11]
	v_mfma_f32_16x16x32_bf16 v[12:15], v[92:95], v[100:103], v[12:15]
	v_mfma_f32_16x16x32_bf16 v[44:47], v[84:87], v[108:111], v[44:47]
	v_mfma_f32_16x16x32_bf16 v[100:103], v[92:95], v[108:111], v[104:107]
	v_mfma_f32_16x16x32_bf16 v[104:107], v[84:87], v[116:119], v[160:163]
	v_mfma_f32_16x16x32_bf16 v[108:111], v[92:95], v[116:119], v[112:115]
	v_mfma_f32_16x16x32_bf16 v[80:83], v[84:87], v[124:127], v[80:83]
	v_mfma_f32_16x16x32_bf16 v[84:87], v[92:95], v[124:127], v[88:91]
	s_setprio 0
	s_add_i32 s51, 0, 0x18000
	v_add_u32_e32 v221, s51, v171
	s_barrier
	ds_read_b128 v[88:91], v221
	ds_read_b128 v[92:95], v221 offset:1024
	ds_read_b128 v[112:115], v221 offset:2048
	ds_read_b128 v[116:119], v221 offset:3072
	s_add_u32 s52, s24, 0x40100
	s_addc_u32 s53, s25, 0
	s_mov_b32 m0, s40
	v_lshl_add_u64 v[196:197], s[52:53], 0, v[150:151]
	ds_read_b128 v[120:123], v174 offset:32768
	ds_read_b128 v[124:127], v174 offset:33792
	ds_read_b128 v[160:163], v174 offset:34816
	ds_read_b128 v[164:167], v174 offset:35840
	ds_read_b128 v[180:183], v174 offset:36864
	ds_read_b128 v[184:187], v174 offset:37888
	ds_read_b128 v[188:191], v174 offset:38912
	ds_read_b128 v[192:195], v174 offset:39936
	global_load_lds_dwordx4 v[196:197], off
	s_mov_b32 m0, s41
	v_lshl_add_u64 v[196:197], s[52:53], 0, v[146:147]
	global_load_lds_dwordx4 v[196:197], off
	s_waitcnt lgkmcnt(8)
	s_barrier
	s_waitcnt lgkmcnt(0)
	s_setprio 1
	v_mfma_f32_16x16x32_bf16 v[48:51], v[88:91], v[120:123], v[48:51]
	v_mfma_f32_16x16x32_bf16 v[52:55], v[112:115], v[120:123], v[52:55]
	v_mfma_f32_16x16x32_bf16 v[56:59], v[88:91], v[160:163], v[56:59]
	v_mfma_f32_16x16x32_bf16 v[60:63], v[112:115], v[160:163], v[60:63]
	v_mfma_f32_16x16x32_bf16 v[64:67], v[88:91], v[180:183], v[64:67]
	v_mfma_f32_16x16x32_bf16 v[68:71], v[112:115], v[180:183], v[68:71]
	v_mfma_f32_16x16x32_bf16 v[72:75], v[88:91], v[188:191], v[72:75]
	v_mfma_f32_16x16x32_bf16 v[76:79], v[112:115], v[188:191], v[76:79]
	v_mfma_f32_16x16x32_bf16 v[48:51], v[92:95], v[124:127], v[48:51]
	v_mfma_f32_16x16x32_bf16 v[52:55], v[116:119], v[124:127], v[52:55]
	v_mfma_f32_16x16x32_bf16 v[56:59], v[92:95], v[164:167], v[56:59]
	v_mfma_f32_16x16x32_bf16 v[60:63], v[116:119], v[164:167], v[60:63]
	v_mfma_f32_16x16x32_bf16 v[64:67], v[92:95], v[184:187], v[64:67]
	v_mfma_f32_16x16x32_bf16 v[68:71], v[116:119], v[184:187], v[68:71]
	v_mfma_f32_16x16x32_bf16 v[72:75], v[92:95], v[192:195], v[72:75]
	v_mfma_f32_16x16x32_bf16 v[76:79], v[116:119], v[192:195], v[76:79]
	s_setprio 0
	s_barrier
	s_add_i32 s54, 0, 0x1c000
	s_add_i32 s53, s51, s37
	v_add_u32_e32 v226, s54, v171
	v_lshl_add_u64 v[168:169], v[168:169], 0, s[12:13]
	s_mov_b32 m0, s53
	s_add_i32 s51, s53, 0x2000
	ds_read_b128 v[196:199], v226
	ds_read_b128 v[200:203], v226 offset:1024
	ds_read_b128 v[204:207], v226 offset:2048
	ds_read_b128 v[208:211], v226 offset:3072
	global_load_lds_dwordx4 v[168:169], off
	s_mov_b32 m0, s51
	v_lshl_add_u64 v[168:169], v[212:213], 0, s[12:13]
	global_load_lds_dwordx4 v[168:169], off
	s_barrier
	s_waitcnt lgkmcnt(0)
	s_setprio 1
	v_mfma_f32_16x16x32_bf16 v[96:99], v[196:199], v[120:123], v[96:99]
	v_mfma_f32_16x16x32_bf16 v[16:19], v[204:207], v[120:123], v[16:19]
	v_mfma_f32_16x16x32_bf16 v[20:23], v[196:199], v[160:163], v[20:23]
	v_mfma_f32_16x16x32_bf16 v[24:27], v[204:207], v[160:163], v[24:27]
	v_mfma_f32_16x16x32_bf16 v[28:31], v[196:199], v[180:183], v[28:31]
	v_mfma_f32_16x16x32_bf16 v[32:35], v[204:207], v[180:183], v[32:35]
	v_mfma_f32_16x16x32_bf16 v[36:39], v[196:199], v[188:191], v[36:39]
	v_mfma_f32_16x16x32_bf16 v[40:43], v[204:207], v[188:191], v[40:43]
	v_mfma_f32_16x16x32_bf16 v[96:99], v[200:203], v[124:127], v[96:99]
	v_mfma_f32_16x16x32_bf16 v[16:19], v[208:211], v[124:127], v[16:19]
	v_mfma_f32_16x16x32_bf16 v[20:23], v[200:203], v[164:167], v[20:23]
	v_mfma_f32_16x16x32_bf16 v[24:27], v[208:211], v[164:167], v[24:27]
	v_mfma_f32_16x16x32_bf16 v[28:31], v[200:203], v[184:187], v[28:31]
	v_mfma_f32_16x16x32_bf16 v[32:35], v[208:211], v[184:187], v[32:35]
	v_mfma_f32_16x16x32_bf16 v[36:39], v[200:203], v[192:195], v[36:39]
	v_mfma_f32_16x16x32_bf16 v[40:43], v[208:211], v[192:195], v[40:43]
	s_setprio 0
	s_mov_b32 m0, s43
	v_lshl_add_u64 v[168:169], v[214:215], 0, s[12:13]
	s_barrier
	ds_read_b128 v[120:123], v174 offset:49152
	ds_read_b128 v[124:127], v174 offset:50176
	ds_read_b128 v[160:163], v174 offset:51200
	ds_read_b128 v[164:167], v174 offset:52224
	ds_read_b128 v[180:183], v174 offset:53248
	ds_read_b128 v[184:187], v174 offset:54272
	ds_read_b128 v[188:191], v174 offset:55296
	ds_read_b128 v[192:195], v174 offset:56320
	global_load_lds_dwordx4 v[168:169], off
	s_mov_b32 m0, s44
	v_lshl_add_u64 v[168:169], v[216:217], 0, s[12:13]
	global_load_lds_dwordx4 v[168:169], off
	s_barrier
	s_waitcnt lgkmcnt(0)
	s_setprio 1
	v_mfma_f32_16x16x32_bf16 v[128:131], v[88:91], v[120:123], v[128:131]
	v_mfma_f32_16x16x32_bf16 v[132:135], v[112:115], v[120:123], v[132:135]
	v_mfma_f32_16x16x32_bf16 v[136:139], v[88:91], v[160:163], v[136:139]
	v_mfma_f32_16x16x32_bf16 v[140:143], v[112:115], v[160:163], v[140:143]
	v_mfma_f32_16x16x32_bf16 v[152:155], v[88:91], v[180:183], v[152:155]
	v_mfma_f32_16x16x32_bf16 v[156:159], v[112:115], v[180:183], v[156:159]
	v_mfma_f32_16x16x32_bf16 v[0:3], v[88:91], v[188:191], v[0:3]
	v_mfma_f32_16x16x32_bf16 v[4:7], v[112:115], v[188:191], v[4:7]
	v_mfma_f32_16x16x32_bf16 v[88:91], v[92:95], v[124:127], v[128:131]
	v_mfma_f32_16x16x32_bf16 v[112:115], v[116:119], v[124:127], v[132:135]
	v_mfma_f32_16x16x32_bf16 v[128:131], v[92:95], v[164:167], v[136:139]
	v_mfma_f32_16x16x32_bf16 v[132:135], v[116:119], v[164:167], v[140:143]
	v_mfma_f32_16x16x32_bf16 v[136:139], v[92:95], v[184:187], v[152:155]
	v_mfma_f32_16x16x32_bf16 v[140:143], v[116:119], v[184:187], v[156:159]
	v_mfma_f32_16x16x32_bf16 v[0:3], v[92:95], v[192:195], v[0:3]
	v_mfma_f32_16x16x32_bf16 v[4:7], v[116:119], v[192:195], v[4:7]
	s_setprio 0
	s_barrier
	s_add_u32 s56, s26, 0x10180
	s_addc_u32 s57, s27, 0
	s_add_i32 s54, s54, s37
	v_lshl_add_u64 v[92:93], s[56:57], 0, v[148:149]
	s_mov_b32 m0, s54
	s_add_i32 s52, s54, 0x2000
	global_load_lds_dwordx4 v[92:93], off
	s_mov_b32 m0, s52
	v_lshl_add_u64 v[92:93], s[56:57], 0, v[144:145]
	global_load_lds_dwordx4 v[92:93], off
	s_waitcnt vmcnt(6)
	s_barrier
	s_setprio 1
	v_mfma_f32_16x16x32_bf16 v[8:11], v[196:199], v[120:123], v[8:11]
	s_and_b64 s[28:29], s[28:29], exec
	s_cselect_b32 s27, s23, s27
	s_cselect_b32 s26, s22, s26
	v_mfma_f32_16x16x32_bf16 v[12:15], v[204:207], v[120:123], v[12:15]
	v_mfma_f32_16x16x32_bf16 v[44:47], v[196:199], v[160:163], v[44:47]
	v_mfma_f32_16x16x32_bf16 v[92:95], v[204:207], v[160:163], v[100:103]
	v_mfma_f32_16x16x32_bf16 v[100:103], v[196:199], v[180:183], v[104:107]
	v_mfma_f32_16x16x32_bf16 v[104:107], v[204:207], v[180:183], v[108:111]
	v_mfma_f32_16x16x32_bf16 v[80:83], v[196:199], v[188:191], v[80:83]
	v_mfma_f32_16x16x32_bf16 v[84:87], v[204:207], v[188:191], v[84:87]
	v_mfma_f32_16x16x32_bf16 v[8:11], v[200:203], v[124:127], v[8:11]
	v_mfma_f32_16x16x32_bf16 v[12:15], v[208:211], v[124:127], v[12:15]
	v_mfma_f32_16x16x32_bf16 v[44:47], v[200:203], v[164:167], v[44:47]
	v_mfma_f32_16x16x32_bf16 v[92:95], v[208:211], v[164:167], v[92:95]
	v_mfma_f32_16x16x32_bf16 v[100:103], v[200:203], v[184:187], v[100:103]
	v_mfma_f32_16x16x32_bf16 v[104:107], v[208:211], v[184:187], v[104:107]
	v_mfma_f32_16x16x32_bf16 v[80:83], v[200:203], v[192:195], v[80:83]
	v_mfma_f32_16x16x32_bf16 v[84:87], v[208:211], v[192:195], v[84:87]
	s_setprio 0
	s_barrier
	ds_read_b128 v[108:111], v173
	ds_read_b128 v[116:119], v173 offset:1024
	ds_read_b128 v[120:123], v173 offset:2048
	ds_read_b128 v[124:127], v173 offset:3072
	s_add_u32 s24, s24, 0x40180
	s_addc_u32 s25, s25, 0
	s_mov_b32 m0, s47
	v_lshl_add_u64 v[168:169], s[24:25], 0, v[150:151]
	ds_read_b128 v[152:155], v174
	ds_read_b128 v[156:159], v174 offset:1024
	ds_read_b128 v[160:163], v174 offset:2048
	ds_read_b128 v[164:167], v174 offset:3072
	ds_read_b128 v[180:183], v174 offset:4096
	ds_read_b128 v[184:187], v174 offset:5120
	ds_read_b128 v[188:191], v174 offset:6144
	ds_read_b128 v[192:195], v174 offset:7168
	global_load_lds_dwordx4 v[168:169], off
	s_mov_b32 m0, s48
	v_lshl_add_u64 v[168:169], s[24:25], 0, v[146:147]
	global_load_lds_dwordx4 v[168:169], off
	s_waitcnt lgkmcnt(8)
	s_barrier
	s_waitcnt lgkmcnt(0)
	s_setprio 1
	v_mfma_f32_16x16x32_bf16 v[48:51], v[108:111], v[152:155], v[48:51]
	v_mfma_f32_16x16x32_bf16 v[52:55], v[120:123], v[152:155], v[52:55]
	v_mfma_f32_16x16x32_bf16 v[56:59], v[108:111], v[160:163], v[56:59]
	v_mfma_f32_16x16x32_bf16 v[60:63], v[120:123], v[160:163], v[60:63]
	v_mfma_f32_16x16x32_bf16 v[64:67], v[108:111], v[180:183], v[64:67]
	v_mfma_f32_16x16x32_bf16 v[68:71], v[120:123], v[180:183], v[68:71]
	v_mfma_f32_16x16x32_bf16 v[72:75], v[108:111], v[188:191], v[72:75]
	v_mfma_f32_16x16x32_bf16 v[76:79], v[120:123], v[188:191], v[76:79]
	v_mfma_f32_16x16x32_bf16 v[48:51], v[116:119], v[156:159], v[48:51]
	v_mfma_f32_16x16x32_bf16 v[52:55], v[124:127], v[156:159], v[52:55]
	v_mfma_f32_16x16x32_bf16 v[56:59], v[116:119], v[164:167], v[56:59]
	v_mfma_f32_16x16x32_bf16 v[60:63], v[124:127], v[164:167], v[60:63]
	v_mfma_f32_16x16x32_bf16 v[64:67], v[116:119], v[184:187], v[64:67]
	v_mfma_f32_16x16x32_bf16 v[68:71], v[124:127], v[184:187], v[68:71]
	v_mfma_f32_16x16x32_bf16 v[72:75], v[116:119], v[192:195], v[72:75]
	v_mfma_f32_16x16x32_bf16 v[76:79], v[124:127], v[192:195], v[76:79]
	s_setprio 0
	s_barrier
	s_mov_b32 m0, s49
	v_lshl_add_u64 v[168:169], s[26:27], 0, v[148:149]
	ds_read_b128 v[196:199], v175
	ds_read_b128 v[200:203], v175 offset:1024
	ds_read_b128 v[204:207], v175 offset:2048
	ds_read_b128 v[208:211], v175 offset:3072
	global_load_lds_dwordx4 v[168:169], off
	s_mov_b32 m0, s50
	v_lshl_add_u64 v[230:231], s[26:27], 0, v[144:145]
	global_load_lds_dwordx4 v[230:231], off
	s_barrier
	s_waitcnt lgkmcnt(0)
	s_setprio 1
	v_mfma_f32_16x16x32_bf16 v[96:99], v[196:199], v[152:155], v[96:99]
	v_mfma_f32_16x16x32_bf16 v[16:19], v[204:207], v[152:155], v[16:19]
	v_mfma_f32_16x16x32_bf16 v[20:23], v[196:199], v[160:163], v[20:23]
	v_mfma_f32_16x16x32_bf16 v[24:27], v[204:207], v[160:163], v[24:27]
	v_mfma_f32_16x16x32_bf16 v[28:31], v[196:199], v[180:183], v[28:31]
	v_mfma_f32_16x16x32_bf16 v[32:35], v[204:207], v[180:183], v[32:35]
	v_mfma_f32_16x16x32_bf16 v[36:39], v[196:199], v[188:191], v[36:39]
	v_mfma_f32_16x16x32_bf16 v[40:43], v[204:207], v[188:191], v[40:43]
	v_mfma_f32_16x16x32_bf16 v[152:155], v[200:203], v[156:159], v[96:99]
	v_mfma_f32_16x16x32_bf16 v[16:19], v[208:211], v[156:159], v[16:19]
	v_mfma_f32_16x16x32_bf16 v[20:23], v[200:203], v[164:167], v[20:23]
	v_mfma_f32_16x16x32_bf16 v[24:27], v[208:211], v[164:167], v[24:27]
	v_mfma_f32_16x16x32_bf16 v[28:31], v[200:203], v[184:187], v[28:31]
	v_mfma_f32_16x16x32_bf16 v[32:35], v[208:211], v[184:187], v[32:35]
	v_mfma_f32_16x16x32_bf16 v[36:39], v[200:203], v[192:195], v[36:39]
	v_mfma_f32_16x16x32_bf16 v[40:43], v[208:211], v[192:195], v[40:43]
	s_setprio 0
	s_mov_b32 m0, s38
	v_lshl_add_u64 v[234:235], s[20:21], 0, v[150:151]
	s_barrier
	ds_read_b128 v[96:99], v174 offset:16384
	ds_read_b128 v[156:159], v174 offset:17408
	ds_read_b128 v[160:163], v174 offset:18432
	ds_read_b128 v[164:167], v174 offset:19456
	ds_read_b128 v[180:183], v174 offset:20480
	ds_read_b128 v[184:187], v174 offset:21504
	ds_read_b128 v[188:191], v174 offset:22528
	ds_read_b128 v[192:195], v174 offset:23552
	global_load_lds_dwordx4 v[234:235], off
	s_mov_b32 m0, s39
	v_lshl_add_u64 v[236:237], s[20:21], 0, v[146:147]
	global_load_lds_dwordx4 v[236:237], off
	s_barrier
	s_waitcnt lgkmcnt(0)
	s_setprio 1
	v_mfma_f32_16x16x32_bf16 v[88:91], v[108:111], v[96:99], v[88:91]
	v_mfma_f32_16x16x32_bf16 v[112:115], v[120:123], v[96:99], v[112:115]
	v_mfma_f32_16x16x32_bf16 v[136:139], v[108:111], v[180:183], v[136:139]
	v_mfma_f32_16x16x32_bf16 v[140:143], v[120:123], v[180:183], v[140:143]
	v_mfma_f32_16x16x32_bf16 v[0:3], v[108:111], v[188:191], v[0:3]
	v_mfma_f32_16x16x32_bf16 v[4:7], v[120:123], v[188:191], v[4:7]
	v_mfma_f32_16x16x32_bf16 v[128:131], v[108:111], v[160:163], v[128:131]
	v_mfma_f32_16x16x32_bf16 v[132:135], v[120:123], v[160:163], v[132:135]
	v_mfma_f32_16x16x32_bf16 v[88:91], v[116:119], v[156:159], v[88:91]
	v_mfma_f32_16x16x32_bf16 v[112:115], v[124:127], v[156:159], v[112:115]
	v_mfma_f32_16x16x32_bf16 v[136:139], v[116:119], v[184:187], v[136:139]
	v_mfma_f32_16x16x32_bf16 v[140:143], v[124:127], v[184:187], v[140:143]
	v_mfma_f32_16x16x32_bf16 v[0:3], v[116:119], v[192:195], v[0:3]
	v_mfma_f32_16x16x32_bf16 v[4:7], v[124:127], v[192:195], v[4:7]
	v_mfma_f32_16x16x32_bf16 v[212:215], v[116:119], v[164:167], v[128:131]
	v_mfma_f32_16x16x32_bf16 v[216:219], v[124:127], v[164:167], v[132:135]
	s_setprio 0
	s_barrier
	s_add_u32 s24, s26, 0x10000
	s_addc_u32 s25, s27, 0
	s_mov_b32 m0, s19
	v_lshl_add_u64 v[108:109], s[24:25], 0, v[148:149]
	global_load_lds_dwordx4 v[108:109], off
	s_mov_b32 m0, s17
	v_lshl_add_u64 v[108:109], s[24:25], 0, v[144:145]
	global_load_lds_dwordx4 v[108:109], off
	s_waitcnt vmcnt(6)
	s_barrier
	s_setprio 1
	v_mfma_f32_16x16x32_bf16 v[8:11], v[196:199], v[96:99], v[8:11]
	v_mfma_f32_16x16x32_bf16 v[12:15], v[204:207], v[96:99], v[12:15]
	v_mfma_f32_16x16x32_bf16 v[44:47], v[196:199], v[160:163], v[44:47]
	v_mfma_f32_16x16x32_bf16 v[92:95], v[204:207], v[160:163], v[92:95]
	v_mfma_f32_16x16x32_bf16 v[96:99], v[196:199], v[180:183], v[100:103]
	v_mfma_f32_16x16x32_bf16 v[100:103], v[204:207], v[180:183], v[104:107]
	v_mfma_f32_16x16x32_bf16 v[80:83], v[196:199], v[188:191], v[80:83]
	v_mfma_f32_16x16x32_bf16 v[84:87], v[204:207], v[188:191], v[84:87]
	v_mfma_f32_16x16x32_bf16 v[124:127], v[200:203], v[156:159], v[8:11]
	v_mfma_f32_16x16x32_bf16 v[156:159], v[208:211], v[156:159], v[12:15]
	v_mfma_f32_16x16x32_bf16 v[160:163], v[200:203], v[164:167], v[44:47]
	v_mfma_f32_16x16x32_bf16 v[164:167], v[208:211], v[164:167], v[92:95]
	v_mfma_f32_16x16x32_bf16 v[180:183], v[200:203], v[184:187], v[96:99]
	v_mfma_f32_16x16x32_bf16 v[100:103], v[208:211], v[184:187], v[100:103]
	v_mfma_f32_16x16x32_bf16 v[184:187], v[200:203], v[192:195], v[80:83]
	v_mfma_f32_16x16x32_bf16 v[188:191], v[208:211], v[192:195], v[84:87]
	s_setprio 0
	s_barrier
	ds_read_b128 v[8:11], v221
	ds_read_b128 v[12:15], v221 offset:1024
	ds_read_b128 v[44:47], v221 offset:2048
	ds_read_b128 v[192:195], v221 offset:3072
	s_add_u32 s24, s20, 0x40000
	s_addc_u32 s25, s21, 0
	s_mov_b32 m0, s40
	v_lshl_add_u64 v[92:93], s[24:25], 0, v[150:151]
	ds_read_b128 v[80:83], v174 offset:32768
	ds_read_b128 v[84:87], v174 offset:33792
	ds_read_b128 v[104:107], v174 offset:34816
	ds_read_b128 v[196:199], v174 offset:35840
	ds_read_b128 v[108:111], v174 offset:36864
	ds_read_b128 v[200:203], v174 offset:37888
	ds_read_b128 v[204:207], v174 offset:38912
	ds_read_b128 v[208:211], v174 offset:39936
	global_load_lds_dwordx4 v[92:93], off
	s_mov_b32 m0, s41
	v_lshl_add_u64 v[92:93], s[24:25], 0, v[146:147]
	global_load_lds_dwordx4 v[92:93], off
	s_waitcnt lgkmcnt(8)
	s_barrier
;     __device__ __forceinline__ void epi(const f32x4 (&acc)[2][2][4][2], const Unit& u, int wr, int wc, int fr, int fq) const {
;     ...
;         const int row0 = u.pm * 256 + wr * 64 + fr, col0 = u.pn * 256 + wc * 32 + 8 * fq;
; #pragma unroll
;         for (int ai = 0; ai < 2; ++ai) {
;             u32x4 xo[4][2];
; #pragma unroll
;             for (int m = 0; m < 4; ++m)
; #pragma unroll
;                 for (int bj = 0; bj < 2; ++bj) xo[m][bj] = *(const u32x4*)(xb + (size_t)(row0 + ai * 128 + m * 16) * D + col0 + bj * 128);
	s_waitcnt lgkmcnt(0)
	s_setprio 1
	v_mfma_f32_16x16x32_bf16 v[52:55], v[44:47], v[80:83], v[52:55]
	v_mfma_f32_16x16x32_bf16 v[56:59], v[8:11], v[104:107], v[56:59]
	v_mfma_f32_16x16x32_bf16 v[60:63], v[44:47], v[104:107], v[60:63]
	v_mfma_f32_16x16x32_bf16 v[64:67], v[8:11], v[108:111], v[64:67]
	v_mfma_f32_16x16x32_bf16 v[68:71], v[44:47], v[108:111], v[68:71]
	v_mfma_f32_16x16x32_bf16 v[72:75], v[8:11], v[204:207], v[72:75]
	v_mfma_f32_16x16x32_bf16 v[222:225], v[44:47], v[204:207], v[76:79]
	v_mfma_f32_16x16x32_bf16 v[48:51], v[8:11], v[80:83], v[48:51]
	v_mfma_f32_16x16x32_bf16 v[128:131], v[192:195], v[84:87], v[52:55]
	v_mfma_f32_16x16x32_bf16 v[120:123], v[12:15], v[196:199], v[56:59]
	v_mfma_f32_16x16x32_bf16 v[116:119], v[192:195], v[196:199], v[60:63]
	v_mfma_f32_16x16x32_bf16 v[96:99], v[12:15], v[200:203], v[64:67]
	v_mfma_f32_16x16x32_bf16 v[92:95], v[192:195], v[200:203], v[68:71]
	v_mfma_f32_16x16x32_bf16 v[76:79], v[12:15], v[208:211], v[72:75]
	v_mfma_f32_16x16x32_bf16 v[72:75], v[192:195], v[208:211], v[222:225]
	v_mfma_f32_16x16x32_bf16 v[132:135], v[12:15], v[84:87], v[48:51]
	s_setprio 0
	s_barrier
	s_mov_b32 m0, s53
	v_lshl_add_u64 v[48:49], v[168:169], 0, s[6:7]
	ds_read_b128 v[56:59], v226
	ds_read_b128 v[222:225], v226 offset:1024
	ds_read_b128 v[60:63], v226 offset:2048
	ds_read_b128 v[226:229], v226 offset:3072
	global_load_lds_dwordx4 v[48:49], off
	s_mov_b32 m0, s51
	v_lshl_add_u64 v[48:49], v[230:231], 0, s[6:7]
	global_load_lds_dwordx4 v[48:49], off
	s_barrier
	s_waitcnt lgkmcnt(0)
	s_setprio 1
	v_mfma_f32_16x16x32_bf16 v[48:51], v[56:59], v[80:83], v[152:155]
	v_mfma_f32_16x16x32_bf16 v[16:19], v[60:63], v[80:83], v[16:19]
	v_mfma_f32_16x16x32_bf16 v[20:23], v[56:59], v[104:107], v[20:23]
	v_mfma_f32_16x16x32_bf16 v[24:27], v[60:63], v[104:107], v[24:27]
	v_mfma_f32_16x16x32_bf16 v[28:31], v[56:59], v[108:111], v[28:31]
	v_mfma_f32_16x16x32_bf16 v[32:35], v[60:63], v[108:111], v[32:35]
	v_mfma_f32_16x16x32_bf16 v[36:39], v[56:59], v[204:207], v[36:39]
	v_mfma_f32_16x16x32_bf16 v[40:43], v[60:63], v[204:207], v[40:43]
	v_mfma_f32_16x16x32_bf16 v[204:207], v[222:225], v[84:87], v[48:51]
	v_mfma_f32_16x16x32_bf16 v[230:233], v[226:229], v[84:87], v[16:19]
	v_mfma_f32_16x16x32_bf16 v[108:111], v[222:225], v[196:199], v[20:23]
	v_mfma_f32_16x16x32_bf16 v[104:107], v[226:229], v[196:199], v[24:27]
	v_mfma_f32_16x16x32_bf16 v[84:87], v[222:225], v[200:203], v[28:31]
	v_mfma_f32_16x16x32_bf16 v[80:83], v[226:229], v[200:203], v[32:35]
	v_mfma_f32_16x16x32_bf16 v[68:71], v[222:225], v[208:211], v[36:39]
	v_mfma_f32_16x16x32_bf16 v[64:67], v[226:229], v[208:211], v[40:43]
	s_setprio 0
	s_mov_b32 m0, s43
	v_lshl_add_u64 v[24:25], v[234:235], 0, s[6:7]
	s_barrier
	ds_read_b128 v[16:19], v174 offset:49152
	ds_read_b128 v[20:23], v174 offset:50176
	ds_read_b128 v[32:35], v174 offset:51200
	ds_read_b128 v[152:155], v174 offset:52224
	ds_read_b128 v[36:39], v174 offset:53248
	ds_read_b128 v[196:199], v174 offset:54272
	ds_read_b128 v[200:203], v174 offset:55296
	ds_read_b128 v[208:211], v174 offset:56320
	global_load_lds_dwordx4 v[24:25], off
	s_mov_b32 m0, s44
	v_lshl_add_u64 v[24:25], v[236:237], 0, s[6:7]
	global_load_lds_dwordx4 v[24:25], off
	s_barrier
	s_waitcnt lgkmcnt(0)
	s_setprio 1
	v_mfma_f32_16x16x32_bf16 v[24:27], v[8:11], v[16:19], v[88:91]
	v_mfma_f32_16x16x32_bf16 v[28:31], v[44:47], v[16:19], v[112:115]
	v_mfma_f32_16x16x32_bf16 v[40:43], v[8:11], v[32:35], v[212:215]
	v_mfma_f32_16x16x32_bf16 v[88:91], v[44:47], v[32:35], v[216:219]
	v_mfma_f32_16x16x32_bf16 v[112:115], v[8:11], v[36:39], v[136:139]
	v_mfma_f32_16x16x32_bf16 v[136:139], v[44:47], v[36:39], v[140:143]
	v_mfma_f32_16x16x32_bf16 v[0:3], v[8:11], v[200:203], v[0:3]
	v_mfma_f32_16x16x32_bf16 v[4:7], v[44:47], v[200:203], v[4:7]
	v_mfma_f32_16x16x32_bf16 v[52:55], v[12:15], v[20:23], v[24:27]
	v_mfma_f32_16x16x32_bf16 v[48:51], v[192:195], v[20:23], v[28:31]
	v_mfma_f32_16x16x32_bf16 v[44:47], v[12:15], v[152:155], v[40:43]
	v_mfma_f32_16x16x32_bf16 v[40:43], v[192:195], v[152:155], v[88:91]
	v_mfma_f32_16x16x32_bf16 v[28:31], v[12:15], v[196:199], v[112:115]
	v_mfma_f32_16x16x32_bf16 v[24:27], v[192:195], v[196:199], v[136:139]
	v_mfma_f32_16x16x32_bf16 v[12:15], v[12:15], v[208:211], v[0:3]
	v_mfma_f32_16x16x32_bf16 v[8:11], v[192:195], v[208:211], v[4:7]
	s_setprio 0
	s_barrier
	s_add_u32 s24, s26, 0x10080
	s_addc_u32 s25, s27, 0
	s_mov_b32 m0, s54
	v_lshl_add_u64 v[0:1], s[24:25], 0, v[148:149]
	global_load_lds_dwordx4 v[0:1], off
	s_mov_b32 m0, s52
	v_lshl_add_u64 v[0:1], s[24:25], 0, v[144:145]
	global_load_lds_dwordx4 v[0:1], off
	s_waitcnt vmcnt(6)
	s_barrier
	s_setprio 1
	v_mfma_f32_16x16x32_bf16 v[0:3], v[56:59], v[16:19], v[124:127]
	v_mfma_f32_16x16x32_bf16 v[4:7], v[60:63], v[16:19], v[156:159]
	v_mfma_f32_16x16x32_bf16 v[16:19], v[56:59], v[32:35], v[160:163]
	v_mfma_f32_16x16x32_bf16 v[32:35], v[60:63], v[32:35], v[164:167]
	v_mfma_f32_16x16x32_bf16 v[88:91], v[56:59], v[36:39], v[180:183]
	v_mfma_f32_16x16x32_bf16 v[100:103], v[60:63], v[36:39], v[100:103]
	v_mfma_f32_16x16x32_bf16 v[112:115], v[56:59], v[200:203], v[184:187]
	v_mfma_f32_16x16x32_bf16 v[124:127], v[60:63], v[200:203], v[188:191]
	v_mfma_f32_16x16x32_bf16 v[60:63], v[222:225], v[20:23], v[0:3]
	v_mfma_f32_16x16x32_bf16 v[56:59], v[226:229], v[20:23], v[4:7]
	v_mfma_f32_16x16x32_bf16 v[36:39], v[222:225], v[152:155], v[16:19]
	v_mfma_f32_16x16x32_bf16 v[32:35], v[226:229], v[152:155], v[32:35]
	v_mfma_f32_16x16x32_bf16 v[20:23], v[222:225], v[196:199], v[88:91]
	v_mfma_f32_16x16x32_bf16 v[16:19], v[226:229], v[196:199], v[100:103]
	v_mfma_f32_16x16x32_bf16 v[4:7], v[222:225], v[208:211], v[112:115]
	v_mfma_f32_16x16x32_bf16 v[0:3], v[226:229], v[208:211], v[124:127]
	s_setprio 0
	v_lshl_or_b32 v152, s45, 8, v172
	v_lshl_add_u32 v156, s8, 8, v170
	v_ashrrev_i32_e32 v153, 31, v152
	v_lshlrev_b64 v[190:191], 1, v[152:153]
	v_ashrrev_i32_e32 v157, 31, v156
	v_lshl_add_u64 v[154:155], s[0:1], 0, v[190:191]
	v_lshlrev_b64 v[192:193], 11, v[156:157]
	v_lshl_add_u64 v[88:89], v[154:155], 0, v[192:193]
	s_barrier
; __device__ __forceinline__ unsigned pk2(float lo, float hi) { unsigned r; asm volatile("v_cvt_pk_bf16_f32 %0, %1, %2" : "=v"(r) : "v"(lo), "v"(hi)); return r; }
; __device__ __forceinline__ unsigned pk2(float lo, float hi) { return f2bf(lo) | (f2bf(hi) << 16); }
;     __device__ __forceinline__ void epi(const f32x4 (&acc)[2][2][4][2], const Unit& u, int wr, int wc, int fr, int fq) const {
;     ...
;         const int row0 = u.pm * 256 + wr * 64 + fr, col0 = u.pn * 256 + wc * 32 + 8 * fq;
; #pragma unroll
;         for (int ai = 0; ai < 2; ++ai) {
;             u32x4 xo[4][2];
; #pragma unroll
;             for (int m = 0; m < 4; ++m)
; #pragma unroll
;                 for (int bj = 0; bj < 2; ++bj) xo[m][bj] = *(const u32x4*)(xb + (size_t)(row0 + ai * 128 + m * 16) * D + col0 + bj * 128);
; #pragma unroll
;             for (int m = 0; m < 4; ++m) {
;                 const int row = row0 + ai * 128 + m * 16; const size_t off = (size_t)row * D + col0; float ss = 0.f;
; #pragma unroll
;                 for (int bj = 0; bj < 2; ++bj) {
;                     const u32x4 o = xo[m][bj]; const f32x4 a0v = acc[ai][bj][m][0], a1v = acc[ai][bj][m][1];
;                     const float v0 = bf_lo(o.x) + coef * a0v[0], v1 = bf_hi(o.x) + coef * a0v[1], v2 = bf_lo(o.y) + coef * a0v[2], v3 = bf_hi(o.y) + coef * a0v[3];
;                     const float v4 = bf_lo(o.z) + coef * a1v[0], v5 = bf_hi(o.z) + coef * a1v[1], v6 = bf_lo(o.w) + coef * a1v[2], v7 = bf_hi(o.w) + coef * a1v[3];
;                     u32x4 w; w.x = pk2(v0, v1); w.y = pk2(v2, v3); w.z = pk2(v4, v5); w.w = pk2(v6, v7);
;                     *(u32x4*)(xb + off + bj * 128) = w;
;                     ss += ((v0 * v0 + v1 * v1) + (v2 * v2 + v3 * v3)) + ((v4 * v4 + v5 * v5) + (v6 * v6 + v7 * v7));
;                 }
;                 ss += __shfl_xor(ss, 16); ss += __shfl_xor(ss, 32);
;                 if (fq == 0) rowss[(size_t)row * 32 + u.pn * 4 + wc] = ss;
	v_mov_b32_e32 v214, 0x40000
	v_mov_b32_e32 v215, 0
	v_lshl_add_u64 v[212:213], v[88:89], 0, v[214:215]
	v_mov_b32_e32 v214, 0x8000
	global_load_dwordx4 v[182:185], v[88:89], off
	global_load_dwordx4 v[186:189], v[88:89], off offset:256
	v_or_b32_e32 v166, 16, v156
	v_or_b32_e32 v162, 32, v156
	v_or_b32_e32 v158, 48, v156
	v_ashrrev_i32_e32 v167, 31, v166
	v_ashrrev_i32_e32 v163, 31, v162
	v_ashrrev_i32_e32 v159, 31, v158
	v_lshlrev_b64 v[168:169], 11, v[166:167]
	v_lshlrev_b64 v[164:165], 11, v[162:163]
	v_lshlrev_b64 v[160:161], 11, v[158:159]
	v_lshl_add_u64 v[88:89], v[154:155], 0, v[168:169]
	v_lshl_add_u64 v[90:91], v[154:155], 0, v[164:165]
	v_lshl_add_u64 v[180:181], v[154:155], 0, v[160:161]
	global_load_dwordx4 v[140:143], v[88:89], off
	global_load_dwordx4 v[136:139], v[88:89], off offset:256
	global_load_dwordx4 v[124:127], v[90:91], off
	global_load_dwordx4 v[112:115], v[90:91], off offset:256
	global_load_dwordx4 v[100:103], v[180:181], off
	s_nop 0
	global_load_dwordx4 v[88:91], v[180:181], off offset:256
	global_load_dwordx4 v[216:219], v[212:213], off
	global_load_dwordx4 v[222:225], v[212:213], off offset:256
	v_lshl_add_u64 v[212:213], v[212:213], 0, v[214:215]
	global_load_dwordx4 v[226:229], v[212:213], off
	global_load_dwordx4 v[234:237], v[212:213], off offset:256
	v_lshl_add_u64 v[212:213], v[212:213], 0, v[214:215]
	global_load_dwordx4 v[238:241], v[212:213], off
	global_load_dwordx4 v[242:245], v[212:213], off offset:256
	v_lshl_add_u64 v[212:213], v[212:213], 0, v[214:215]
	global_load_dwordx4 v[246:249], v[212:213], off
	global_load_dwordx4 v[250:253], v[212:213], off offset:256
	v_lshl_add_u64 v[192:193], s[0:1], 0, v[192:193]
	v_lshl_add_u64 v[190:191], v[192:193], 0, v[190:191]
	v_cmp_lt_i32_e32 vcc, v177, v178
	s_waitcnt vmcnt(8)
	v_lshlrev_b32_e32 v181, 16, v182
	v_and_b32_e32 v182, 0xffff0000, v182
	v_lshlrev_b32_e32 v192, 16, v183
	v_and_b32_e32 v183, 0xffff0000, v183
	v_lshlrev_b32_e32 v193, 16, v184
	v_and_b32_e32 v184, 0xffff0000, v184
	v_lshlrev_b32_e32 v194, 16, v185
	v_and_b32_e32 v185, 0xffff0000, v185
	v_lshlrev_b32_e32 v195, 16, v186
	v_and_b32_e32 v186, 0xffff0000, v186
	v_lshlrev_b32_e32 v196, 16, v187
	v_and_b32_e32 v187, 0xffff0000, v187
	v_lshlrev_b32_e32 v197, 16, v188
	v_and_b32_e32 v188, 0xffff0000, v188
	v_lshlrev_b32_e32 v198, 16, v189
	v_and_b32_e32 v189, 0xffff0000, v189
	v_add_f32_e32 v133, v133, v182
	v_add_f32_e32 v135, v135, v183
	v_add_f32_e32 v182, v129, v184
	v_add_f32_e32 v131, v131, v185
	v_add_f32_e32 v185, v205, v186
	v_add_f32_e32 v187, v207, v187
	v_add_f32_e32 v188, v231, v188
	v_add_f32_e32 v189, v233, v189
	v_add_f32_e32 v132, v132, v181
	v_add_f32_e32 v134, v134, v192
	v_add_f32_e32 v181, v128, v193
	v_add_f32_e32 v183, v130, v194
	v_add_f32_e32 v184, v204, v195
	v_add_f32_e32 v186, v206, v196
	v_add_f32_e32 v192, v230, v197
	v_add_f32_e32 v193, v232, v198
	v_cvt_pk_bf16_f32 v128, v132, v133
	v_cvt_pk_bf16_f32 v129, v134, v135
	v_mul_f32_e32 v130, v133, v133
	v_mul_f32_e32 v133, v135, v135
	v_mul_f32_e32 v135, v182, v182
	v_mul_f32_e32 v194, v131, v131
	v_mul_f32_e32 v195, v185, v185
	v_mul_f32_e32 v196, v187, v187
	v_mul_f32_e32 v197, v188, v188
	v_mul_f32_e32 v198, v189, v189
	v_fmac_f32_e32 v130, v132, v132
	v_fmac_f32_e32 v133, v134, v134
	v_fmac_f32_e32 v135, v181, v181
	v_fmac_f32_e32 v194, v183, v183
	v_fmac_f32_e32 v195, v184, v184
	v_fmac_f32_e32 v196, v186, v186
	v_fmac_f32_e32 v197, v192, v192
	v_fmac_f32_e32 v198, v193, v193
	v_add_f32_e32 v130, v130, v133
	v_add_f32_e32 v132, v135, v194
	v_add_f32_e32 v133, v195, v196
	v_add_f32_e32 v134, v197, v198
	v_cndmask_b32_e32 v180, v176, v177, vcc
	v_add_f32_e32 v130, v130, v132
	v_add_f32_e32 v132, v133, v134
	v_lshlrev_b32_e32 v180, 2, v180
	v_add_f32_e32 v133, v130, v132
	ds_bpermute_b32 v134, v180, v133
	v_cmp_lt_i32_e32 vcc, v179, v178
	v_cvt_pk_bf16_f32 v130, v181, v182
	v_cvt_pk_bf16_f32 v131, v183, v131
	global_store_dwordx4 v[190:191], v[128:131], off
	v_cvt_pk_bf16_f32 v132, v184, v185
	s_nop 1
	v_cndmask_b32_e32 v128, v176, v179, vcc
	s_waitcnt lgkmcnt(0)
	v_add_f32_e32 v129, v133, v134
	v_lshlrev_b32_e32 v128, 2, v128
	ds_bpermute_b32 v130, v128, v129
	v_cvt_pk_bf16_f32 v133, v186, v187
	v_cvt_pk_bf16_f32 v134, v192, v188
	v_cvt_pk_bf16_f32 v135, v193, v189
	global_store_dwordx4 v[190:191], v[132:135], off offset:256
	s_and_saveexec_b64 s[24:25], s[4:5]
	s_cbranch_execz .LBB0_1672
	s_waitcnt lgkmcnt(0)
	v_add_f32_e32 v129, v129, v130
	s_lshl_b32 s26, s45, 2
	v_lshlrev_b64 v[130:131], 7, v[156:157]
	s_ashr_i32 s27, s26, 31
	v_lshl_add_u64 v[130:131], s[2:3], 0, v[130:131]
	v_lshl_add_u64 v[130:131], s[26:27], 2, v[130:131]
	s_lshl_b32 s8, s42, 2
	v_lshl_add_u64 v[130:131], v[130:131], 0, s[8:9]
	global_store_dword v[130:131], v129, off

.LBB0_1906:
	ds_read_b128 v[134:137], v185
	ds_read_b128 v[138:141], v185 offset:1024
	ds_read_b128 v[142:145], v185 offset:2048
	ds_read_b128 v[146:149], v185 offset:3072
	s_mov_b32 m0, s45
	v_lshl_add_u64 v[150:151], v[128:129], 0, s[24:25]
	ds_read_b128 v[164:167], v186
	ds_read_b128 v[168:171], v186 offset:1024
	ds_read_b128 v[172:175], v186 offset:2048
	ds_read_b128 v[176:179], v186 offset:3072
	ds_read_b128 v[190:193], v186 offset:4096
	ds_read_b128 v[194:197], v186 offset:5120
	ds_read_b128 v[198:201], v186 offset:6144
	ds_read_b128 v[202:205], v186 offset:7168
	global_load_lds_dwordx4 v[150:151], off
	s_mov_b32 m0, s46
	v_lshl_add_u64 v[150:151], v[130:131], 0, s[24:25]
	global_load_lds_dwordx4 v[150:151], off
	s_waitcnt lgkmcnt(8)
	s_barrier
	s_waitcnt lgkmcnt(0)
	s_setprio 1
	v_mfma_f32_16x16x32_bf16 v[116:119], v[134:137], v[164:167], v[116:119]
	s_add_i32 s26, s24, 0xfff50080
	v_mfma_f32_16x16x32_bf16 v[112:115], v[142:145], v[164:167], v[112:115]
	s_cmp_eq_u32 s58, 40
	v_mfma_f32_16x16x32_bf16 v[108:111], v[134:137], v[172:175], v[108:111]
	s_cselect_b32 s59, s19, s21
	v_mfma_f32_16x16x32_bf16 v[104:107], v[142:145], v[172:175], v[104:107]
	s_cselect_b32 s60, s18, s20
	v_mfma_f32_16x16x32_bf16 v[92:95], v[134:137], v[190:193], v[92:95]
	s_cselect_b32 s27, s7, s23
	v_mfma_f32_16x16x32_bf16 v[88:91], v[142:145], v[190:193], v[88:91]
	s_cselect_b32 s61, s6, s22
	v_mfma_f32_16x16x32_bf16 v[76:79], v[134:137], v[198:201], v[76:79]
	v_mfma_f32_16x16x32_bf16 v[72:75], v[142:145], v[198:201], v[72:75]
	v_mfma_f32_16x16x32_bf16 v[116:119], v[138:141], v[168:171], v[116:119]
	v_mfma_f32_16x16x32_bf16 v[112:115], v[146:149], v[168:171], v[112:115]
	v_mfma_f32_16x16x32_bf16 v[108:111], v[138:141], v[176:179], v[108:111]
	v_mfma_f32_16x16x32_bf16 v[104:107], v[146:149], v[176:179], v[104:107]
	v_mfma_f32_16x16x32_bf16 v[92:95], v[138:141], v[194:197], v[92:95]
	v_mfma_f32_16x16x32_bf16 v[88:91], v[146:149], v[194:197], v[88:91]
	v_mfma_f32_16x16x32_bf16 v[76:79], v[138:141], v[202:205], v[76:79]
	v_mfma_f32_16x16x32_bf16 v[72:75], v[146:149], v[202:205], v[72:75]
	s_setprio 0
	s_barrier
	s_cselect_b32 s62, 0, s26
	s_add_u32 s26, s61, s62
	s_addc_u32 s27, s27, 0
	s_mov_b32 m0, s47
	v_lshl_add_u64 v[150:151], s[26:27], 0, v[154:155]
	ds_read_b128 v[206:209], v187
	ds_read_b128 v[210:213], v187 offset:1024
	ds_read_b128 v[214:217], v187 offset:2048
	ds_read_b128 v[222:225], v187 offset:3072
	global_load_lds_dwordx4 v[150:151], off
	s_mov_b32 m0, s48
	v_lshl_add_u64 v[180:181], s[26:27], 0, v[158:159]
	global_load_lds_dwordx4 v[180:181], off
	s_barrier
	s_waitcnt lgkmcnt(0)
	s_setprio 1
	v_mfma_f32_16x16x32_bf16 v[124:127], v[206:209], v[164:167], v[124:127]
	v_mfma_f32_16x16x32_bf16 v[120:123], v[214:217], v[164:167], v[120:123]
	v_mfma_f32_16x16x32_bf16 v[100:103], v[206:209], v[172:175], v[100:103]
	v_mfma_f32_16x16x32_bf16 v[96:99], v[214:217], v[172:175], v[96:99]
	v_mfma_f32_16x16x32_bf16 v[84:87], v[206:209], v[190:193], v[84:87]
	v_mfma_f32_16x16x32_bf16 v[80:83], v[214:217], v[190:193], v[80:83]
	v_mfma_f32_16x16x32_bf16 v[68:71], v[206:209], v[198:201], v[68:71]
	v_mfma_f32_16x16x32_bf16 v[64:67], v[214:217], v[198:201], v[64:67]
	v_mfma_f32_16x16x32_bf16 v[124:127], v[210:213], v[168:171], v[124:127]
	v_mfma_f32_16x16x32_bf16 v[120:123], v[222:225], v[168:171], v[120:123]
	v_mfma_f32_16x16x32_bf16 v[100:103], v[210:213], v[176:179], v[100:103]
	v_mfma_f32_16x16x32_bf16 v[96:99], v[222:225], v[176:179], v[96:99]
	v_mfma_f32_16x16x32_bf16 v[84:87], v[210:213], v[194:197], v[84:87]
	v_mfma_f32_16x16x32_bf16 v[80:83], v[222:225], v[194:197], v[80:83]
	v_mfma_f32_16x16x32_bf16 v[68:71], v[210:213], v[202:205], v[68:71]
	v_mfma_f32_16x16x32_bf16 v[64:67], v[222:225], v[202:205], v[64:67]
	s_setprio 0
	s_add_u32 s60, s60, s62
	s_addc_u32 s61, s59, 0
	s_mov_b32 m0, s37
	v_lshl_add_u64 v[218:219], s[60:61], 0, v[152:153]
	s_barrier
	ds_read_b128 v[164:167], v186 offset:16384
	ds_read_b128 v[168:171], v186 offset:17408
	ds_read_b128 v[172:175], v186 offset:18432
	ds_read_b128 v[176:179], v186 offset:19456
	ds_read_b128 v[190:193], v186 offset:20480
	ds_read_b128 v[194:197], v186 offset:21504
	ds_read_b128 v[198:201], v186 offset:22528
	ds_read_b128 v[202:205], v186 offset:23552
	global_load_lds_dwordx4 v[218:219], off
	s_mov_b32 m0, s38
	v_lshl_add_u64 v[226:227], s[60:61], 0, v[156:157]
	global_load_lds_dwordx4 v[226:227], off
	s_barrier
	s_waitcnt lgkmcnt(0)
	s_setprio 1
	v_mfma_f32_16x16x32_bf16 v[52:55], v[134:137], v[164:167], v[52:55]
	v_mfma_f32_16x16x32_bf16 v[48:51], v[142:145], v[164:167], v[48:51]
	v_mfma_f32_16x16x32_bf16 v[44:47], v[134:137], v[172:175], v[44:47]
	v_mfma_f32_16x16x32_bf16 v[36:39], v[142:145], v[172:175], v[36:39]
	v_mfma_f32_16x16x32_bf16 v[28:31], v[134:137], v[190:193], v[28:31]
	v_mfma_f32_16x16x32_bf16 v[20:23], v[142:145], v[190:193], v[20:23]
	v_mfma_f32_16x16x32_bf16 v[12:15], v[134:137], v[198:201], v[12:15]
	v_mfma_f32_16x16x32_bf16 v[4:7], v[142:145], v[198:201], v[4:7]
	v_mfma_f32_16x16x32_bf16 v[52:55], v[138:141], v[168:171], v[52:55]
	v_mfma_f32_16x16x32_bf16 v[48:51], v[146:149], v[168:171], v[48:51]
	v_mfma_f32_16x16x32_bf16 v[44:47], v[138:141], v[176:179], v[44:47]
	v_mfma_f32_16x16x32_bf16 v[36:39], v[146:149], v[176:179], v[36:39]
	v_mfma_f32_16x16x32_bf16 v[28:31], v[138:141], v[194:197], v[28:31]
	v_mfma_f32_16x16x32_bf16 v[20:23], v[146:149], v[194:197], v[20:23]
	v_mfma_f32_16x16x32_bf16 v[12:15], v[138:141], v[202:205], v[12:15]
	v_mfma_f32_16x16x32_bf16 v[4:7], v[146:149], v[202:205], v[4:7]
	s_setprio 0
	s_barrier
	s_add_u32 s62, s26, 0xb0000
	s_addc_u32 s63, s27, 0
	s_mov_b32 m0, s52
	v_lshl_add_u64 v[134:135], s[62:63], 0, v[154:155]
	global_load_lds_dwordx4 v[134:135], off
	s_mov_b32 m0, s53
	v_lshl_add_u64 v[134:135], s[62:63], 0, v[158:159]
	global_load_lds_dwordx4 v[134:135], off
	s_waitcnt vmcnt(6)
	s_barrier
	s_setprio 1
	v_mfma_f32_16x16x32_bf16 v[60:63], v[206:209], v[164:167], v[60:63]
	v_mfma_f32_16x16x32_bf16 v[56:59], v[214:217], v[164:167], v[56:59]
	v_mfma_f32_16x16x32_bf16 v[40:43], v[206:209], v[172:175], v[40:43]
	v_mfma_f32_16x16x32_bf16 v[32:35], v[214:217], v[172:175], v[32:35]
	v_mfma_f32_16x16x32_bf16 v[24:27], v[206:209], v[190:193], v[24:27]
	v_mfma_f32_16x16x32_bf16 v[16:19], v[214:217], v[190:193], v[16:19]
	v_mfma_f32_16x16x32_bf16 v[8:11], v[206:209], v[198:201], v[8:11]
	v_mfma_f32_16x16x32_bf16 v[0:3], v[214:217], v[198:201], v[0:3]
	v_mfma_f32_16x16x32_bf16 v[60:63], v[210:213], v[168:171], v[60:63]
	v_mfma_f32_16x16x32_bf16 v[56:59], v[222:225], v[168:171], v[56:59]
	v_mfma_f32_16x16x32_bf16 v[40:43], v[210:213], v[176:179], v[40:43]
	v_mfma_f32_16x16x32_bf16 v[32:35], v[222:225], v[176:179], v[32:35]
	v_mfma_f32_16x16x32_bf16 v[24:27], v[210:213], v[194:197], v[24:27]
	v_mfma_f32_16x16x32_bf16 v[16:19], v[222:225], v[194:197], v[16:19]
	v_mfma_f32_16x16x32_bf16 v[8:11], v[210:213], v[202:205], v[8:11]
	v_mfma_f32_16x16x32_bf16 v[0:3], v[222:225], v[202:205], v[0:3]
	s_setprio 0
	s_barrier
	ds_read_b128 v[134:137], v132
	ds_read_b128 v[138:141], v132 offset:1024
	ds_read_b128 v[142:145], v132 offset:2048
	ds_read_b128 v[146:149], v132 offset:3072
	s_add_u32 s60, s60, 0xb0000
	s_addc_u32 s61, s61, 0
	s_mov_b32 m0, s39
	v_lshl_add_u64 v[206:207], s[60:61], 0, v[152:153]
	ds_read_b128 v[164:167], v186 offset:32768
	ds_read_b128 v[168:171], v186 offset:33792
	ds_read_b128 v[172:175], v186 offset:34816
	ds_read_b128 v[176:179], v186 offset:35840
	ds_read_b128 v[190:193], v186 offset:36864
	ds_read_b128 v[194:197], v186 offset:37888
	ds_read_b128 v[198:201], v186 offset:38912
	ds_read_b128 v[202:205], v186 offset:39936
	global_load_lds_dwordx4 v[206:207], off
	s_mov_b32 m0, s40
	v_lshl_add_u64 v[206:207], s[60:61], 0, v[156:157]
	global_load_lds_dwordx4 v[206:207], off
	s_waitcnt lgkmcnt(8)
	s_barrier
	s_waitcnt lgkmcnt(0)
	s_setprio 1
	v_mfma_f32_16x16x32_bf16 v[116:119], v[134:137], v[164:167], v[116:119]
	v_mfma_f32_16x16x32_bf16 v[112:115], v[142:145], v[164:167], v[112:115]
	v_mfma_f32_16x16x32_bf16 v[108:111], v[134:137], v[172:175], v[108:111]
	v_mfma_f32_16x16x32_bf16 v[104:107], v[142:145], v[172:175], v[104:107]
	v_mfma_f32_16x16x32_bf16 v[92:95], v[134:137], v[190:193], v[92:95]
	v_mfma_f32_16x16x32_bf16 v[88:91], v[142:145], v[190:193], v[88:91]
	v_mfma_f32_16x16x32_bf16 v[76:79], v[134:137], v[198:201], v[76:79]
	v_mfma_f32_16x16x32_bf16 v[72:75], v[142:145], v[198:201], v[72:75]
	v_mfma_f32_16x16x32_bf16 v[116:119], v[138:141], v[168:171], v[116:119]
	v_mfma_f32_16x16x32_bf16 v[112:115], v[146:149], v[168:171], v[112:115]
	v_mfma_f32_16x16x32_bf16 v[108:111], v[138:141], v[176:179], v[108:111]
	v_mfma_f32_16x16x32_bf16 v[104:107], v[146:149], v[176:179], v[104:107]
	v_mfma_f32_16x16x32_bf16 v[92:95], v[138:141], v[194:197], v[92:95]
	v_mfma_f32_16x16x32_bf16 v[88:91], v[146:149], v[194:197], v[88:91]
	v_mfma_f32_16x16x32_bf16 v[76:79], v[138:141], v[202:205], v[76:79]
	v_mfma_f32_16x16x32_bf16 v[72:75], v[146:149], v[202:205], v[72:75]
	s_setprio 0
	s_barrier
	s_mov_b32 m0, s54
	v_lshl_add_u64 v[150:151], v[150:151], 0, s[10:11]
	ds_read_b128 v[206:209], v133
	ds_read_b128 v[210:213], v133 offset:1024
	ds_read_b128 v[214:217], v133 offset:2048
	ds_read_b128 v[222:225], v133 offset:3072
	global_load_lds_dwordx4 v[150:151], off
	s_mov_b32 m0, s55
	v_lshl_add_u64 v[150:151], v[180:181], 0, s[10:11]
	global_load_lds_dwordx4 v[150:151], off
	s_barrier
	s_waitcnt lgkmcnt(0)
	s_setprio 1
	v_mfma_f32_16x16x32_bf16 v[124:127], v[206:209], v[164:167], v[124:127]
	v_mfma_f32_16x16x32_bf16 v[120:123], v[214:217], v[164:167], v[120:123]
	v_mfma_f32_16x16x32_bf16 v[100:103], v[206:209], v[172:175], v[100:103]
	v_mfma_f32_16x16x32_bf16 v[96:99], v[214:217], v[172:175], v[96:99]
	v_mfma_f32_16x16x32_bf16 v[84:87], v[206:209], v[190:193], v[84:87]
	v_mfma_f32_16x16x32_bf16 v[80:83], v[214:217], v[190:193], v[80:83]
	v_mfma_f32_16x16x32_bf16 v[68:71], v[206:209], v[198:201], v[68:71]
	v_mfma_f32_16x16x32_bf16 v[64:67], v[214:217], v[198:201], v[64:67]
	v_mfma_f32_16x16x32_bf16 v[124:127], v[210:213], v[168:171], v[124:127]
	v_mfma_f32_16x16x32_bf16 v[120:123], v[222:225], v[168:171], v[120:123]
	v_mfma_f32_16x16x32_bf16 v[100:103], v[210:213], v[176:179], v[100:103]
	v_mfma_f32_16x16x32_bf16 v[96:99], v[222:225], v[176:179], v[96:99]
	v_mfma_f32_16x16x32_bf16 v[84:87], v[210:213], v[194:197], v[84:87]
	v_mfma_f32_16x16x32_bf16 v[80:83], v[222:225], v[194:197], v[80:83]
	v_mfma_f32_16x16x32_bf16 v[68:71], v[210:213], v[202:205], v[68:71]
	v_mfma_f32_16x16x32_bf16 v[64:67], v[222:225], v[202:205], v[64:67]
	s_setprio 0
	s_mov_b32 m0, s42
	v_lshl_add_u64 v[150:151], v[218:219], 0, s[10:11]
	s_barrier
	ds_read_b128 v[164:167], v186 offset:49152
	ds_read_b128 v[168:171], v186 offset:50176
	ds_read_b128 v[172:175], v186 offset:51200
	ds_read_b128 v[176:179], v186 offset:52224
	ds_read_b128 v[190:193], v186 offset:53248
	ds_read_b128 v[194:197], v186 offset:54272
	ds_read_b128 v[198:201], v186 offset:55296
	ds_read_b128 v[202:205], v186 offset:56320
	global_load_lds_dwordx4 v[150:151], off
	s_mov_b32 m0, s43
	v_lshl_add_u64 v[150:151], v[226:227], 0, s[10:11]
	global_load_lds_dwordx4 v[150:151], off
	s_barrier
;     ...
;         G_PAIR(0, 1);
; #pragma unroll 1
;         for (int t = 2; t < nt; t += 2) G_PAIR(t, 0);
	s_waitcnt lgkmcnt(0)
	s_setprio 1
	v_mfma_f32_16x16x32_bf16 v[52:55], v[134:137], v[164:167], v[52:55]
	v_mfma_f32_16x16x32_bf16 v[48:51], v[142:145], v[164:167], v[48:51]
	v_mfma_f32_16x16x32_bf16 v[44:47], v[134:137], v[172:175], v[44:47]
	v_mfma_f32_16x16x32_bf16 v[36:39], v[142:145], v[172:175], v[36:39]
	v_mfma_f32_16x16x32_bf16 v[28:31], v[134:137], v[190:193], v[28:31]
	v_mfma_f32_16x16x32_bf16 v[20:23], v[142:145], v[190:193], v[20:23]
	v_mfma_f32_16x16x32_bf16 v[12:15], v[134:137], v[198:201], v[12:15]
	v_mfma_f32_16x16x32_bf16 v[4:7], v[142:145], v[198:201], v[4:7]
	v_mfma_f32_16x16x32_bf16 v[52:55], v[138:141], v[168:171], v[52:55]
	v_mfma_f32_16x16x32_bf16 v[48:51], v[146:149], v[168:171], v[48:51]
	v_mfma_f32_16x16x32_bf16 v[44:47], v[138:141], v[176:179], v[44:47]
	v_mfma_f32_16x16x32_bf16 v[36:39], v[146:149], v[176:179], v[36:39]
	v_mfma_f32_16x16x32_bf16 v[28:31], v[138:141], v[194:197], v[28:31]
	v_mfma_f32_16x16x32_bf16 v[20:23], v[146:149], v[194:197], v[20:23]
	v_mfma_f32_16x16x32_bf16 v[12:15], v[138:141], v[202:205], v[12:15]
	v_mfma_f32_16x16x32_bf16 v[4:7], v[146:149], v[202:205], v[4:7]
	s_setprio 0
	s_barrier
	s_add_u32 s26, s26, 0xb0080
	s_addc_u32 s27, s27, 0
	s_mov_b32 m0, s56
	v_lshl_add_u64 v[134:135], s[26:27], 0, v[154:155]
	global_load_lds_dwordx4 v[134:135], off
	s_mov_b32 m0, s57
	v_lshl_add_u64 v[134:135], s[26:27], 0, v[158:159]
	global_load_lds_dwordx4 v[134:135], off
	s_waitcnt vmcnt(6)
	s_barrier
	s_setprio 1
	v_mfma_f32_16x16x32_bf16 v[60:63], v[206:209], v[164:167], v[60:63]
	v_mfma_f32_16x16x32_bf16 v[56:59], v[214:217], v[164:167], v[56:59]
	v_mfma_f32_16x16x32_bf16 v[40:43], v[206:209], v[172:175], v[40:43]
	v_mfma_f32_16x16x32_bf16 v[32:35], v[214:217], v[172:175], v[32:35]
	v_mfma_f32_16x16x32_bf16 v[24:27], v[206:209], v[190:193], v[24:27]
	v_mfma_f32_16x16x32_bf16 v[16:19], v[214:217], v[190:193], v[16:19]
	v_mfma_f32_16x16x32_bf16 v[8:11], v[206:209], v[198:201], v[8:11]
	v_mfma_f32_16x16x32_bf16 v[0:3], v[214:217], v[198:201], v[0:3]
	v_mfma_f32_16x16x32_bf16 v[60:63], v[210:213], v[168:171], v[60:63]
	v_mfma_f32_16x16x32_bf16 v[56:59], v[222:225], v[168:171], v[56:59]
	v_mfma_f32_16x16x32_bf16 v[40:43], v[210:213], v[176:179], v[40:43]
	v_mfma_f32_16x16x32_bf16 v[32:35], v[222:225], v[176:179], v[32:35]
	v_mfma_f32_16x16x32_bf16 v[24:27], v[210:213], v[194:197], v[24:27]
	v_mfma_f32_16x16x32_bf16 v[16:19], v[222:225], v[194:197], v[16:19]
	v_mfma_f32_16x16x32_bf16 v[8:11], v[210:213], v[202:205], v[8:11]
	v_mfma_f32_16x16x32_bf16 v[0:3], v[222:225], v[202:205], v[0:3]
	s_setprio 0
	s_add_i32 s58, s58, 2
	s_add_u32 s24, s24, 0x100
	s_addc_u32 s25, s25, 0
	s_cmp_gt_u32 s58, 41
	s_barrier
	s_cbranch_scc0 .LBB0_1906
; __device__ __forceinline__ unsigned pk2(float lo, float hi) { unsigned r; asm volatile("v_cvt_pk_bf16_f32 %0, %1, %2" : "=v"(r) : "v"(lo), "v"(hi)); return r; }
; __device__ __forceinline__ unsigned pk2(float lo, float hi) { return f2bf(lo) | (f2bf(hi) << 16); }
;     __device__ __forceinline__ void epi(const f32x4 (&acc)[2][2][4][2], const Unit& u, int wr, int wc, int fr, int fq) const {
;     ...
;         const int row0 = u.pm * 256 + wr * 64 + fr, col0 = u.pn * 256 + wc * 32 + 8 * fq;
; #pragma unroll
;         for (int ai = 0; ai < 2; ++ai) {
;             u32x4 xo[4][2];
; #pragma unroll
;             for (int m = 0; m < 4; ++m)
; #pragma unroll
;                 for (int bj = 0; bj < 2; ++bj) xo[m][bj] = *(const u32x4*)(xb + (size_t)(row0 + ai * 128 + m * 16) * D + col0 + bj * 128);
; #pragma unroll
;             for (int m = 0; m < 4; ++m) {
;                 const int row = row0 + ai * 128 + m * 16; const size_t off = (size_t)row * D + col0; float ss = 0.f;
; #pragma unroll
;                 for (int bj = 0; bj < 2; ++bj) {
;                     const u32x4 o = xo[m][bj]; const f32x4 a0v = acc[ai][bj][m][0], a1v = acc[ai][bj][m][1];
;                     const float v0 = bf_lo(o.x) + coef * a0v[0], v1 = bf_hi(o.x) + coef * a0v[1], v2 = bf_lo(o.y) + coef * a0v[2], v3 = bf_hi(o.y) + coef * a0v[3];
;                     const float v4 = bf_lo(o.z) + coef * a1v[0], v5 = bf_hi(o.z) + coef * a1v[1], v6 = bf_lo(o.w) + coef * a1v[2], v7 = bf_hi(o.w) + coef * a1v[3];
;                     u32x4 w; w.x = pk2(v0, v1); w.y = pk2(v2, v3); w.z = pk2(v4, v5); w.w = pk2(v6, v7);
;                     *(u32x4*)(xb + off + bj * 128) = w;
;                     ss += ((v0 * v0 + v1 * v1) + (v2 * v2 + v3 * v3)) + ((v4 * v4 + v5 * v5) + (v6 * v6 + v7 * v7));
;                 }
;                 ss += __shfl_xor(ss, 16); ss += __shfl_xor(ss, 32);
;                 if (fq == 0) rowss[(size_t)row * 32 + u.pn * 4 + wc] = ss;
	v_lshl_or_b32 v164, s30, 8, v184
	v_lshl_add_u32 v168, s2, 8, v182
	v_ashrrev_i32_e32 v165, 31, v164
	v_lshlrev_b64 v[198:199], 1, v[164:165]
	v_ashrrev_i32_e32 v169, 31, v168
	v_lshl_add_u64 v[166:167], s[0:1], 0, v[198:199]
	v_lshlrev_b64 v[200:201], 11, v[168:169]
	v_lshl_add_u64 v[128:129], v[166:167], 0, v[200:201]
	v_mov_b32_e32 v218, 0x40000
	v_mov_b32_e32 v219, 0
	v_lshl_add_u64 v[216:217], v[128:129], 0, v[218:219]
	v_mov_b32_e32 v218, 0x8000
	global_load_dwordx4 v[190:193], v[128:129], off
	global_load_dwordx4 v[194:197], v[128:129], off offset:256
	v_or_b32_e32 v178, 16, v168
	v_or_b32_e32 v174, 32, v168
	v_or_b32_e32 v170, 48, v168
	v_ashrrev_i32_e32 v179, 31, v178
	v_ashrrev_i32_e32 v175, 31, v174
	v_ashrrev_i32_e32 v171, 31, v170
	v_lshlrev_b64 v[180:181], 11, v[178:179]
	v_lshlrev_b64 v[176:177], 11, v[174:175]
	v_lshlrev_b64 v[172:173], 11, v[170:171]
	v_lshl_add_u64 v[128:129], v[166:167], 0, v[180:181]
	v_lshl_add_u64 v[130:131], v[166:167], 0, v[176:177]
	v_lshl_add_u64 v[202:203], v[166:167], 0, v[172:173]
	global_load_dwordx4 v[148:151], v[128:129], off
	global_load_dwordx4 v[144:147], v[128:129], off offset:256
	global_load_dwordx4 v[140:143], v[130:131], off
	global_load_dwordx4 v[136:139], v[130:131], off offset:256
	global_load_dwordx4 v[132:135], v[202:203], off
	s_nop 0
	global_load_dwordx4 v[128:131], v[202:203], off offset:256
	global_load_dwordx4 v[222:225], v[216:217], off
	global_load_dwordx4 v[226:229], v[216:217], off offset:256
	v_lshl_add_u64 v[216:217], v[216:217], 0, v[218:219]
	global_load_dwordx4 v[230:233], v[216:217], off
	global_load_dwordx4 v[234:237], v[216:217], off offset:256
	v_lshl_add_u64 v[216:217], v[216:217], 0, v[218:219]
	global_load_dwordx4 v[238:241], v[216:217], off
	global_load_dwordx4 v[242:245], v[216:217], off offset:256
	v_lshl_add_u64 v[216:217], v[216:217], 0, v[218:219]
	global_load_dwordx4 v[246:249], v[216:217], off
	global_load_dwordx4 v[250:253], v[216:217], off offset:256
	v_and_b32_e32 v202, 64, v188
	v_xor_b32_e32 v189, 16, v188
	v_add_u32_e32 v202, 64, v202
	v_cmp_lt_i32_e32 vcc, v189, v202
	s_waitcnt vmcnt(8)
	v_lshlrev_b32_e32 v203, 16, v190
	v_and_b32_e32 v190, 0xffff0000, v190
	v_lshlrev_b32_e32 v204, 16, v191
	v_and_b32_e32 v191, 0xffff0000, v191
	v_lshlrev_b32_e32 v205, 16, v192
	v_and_b32_e32 v192, 0xffff0000, v192
	v_lshlrev_b32_e32 v206, 16, v193
	v_and_b32_e32 v193, 0xffff0000, v193
	v_lshlrev_b32_e32 v207, 16, v194
	v_and_b32_e32 v194, 0xffff0000, v194
	v_lshlrev_b32_e32 v208, 16, v195
	v_and_b32_e32 v195, 0xffff0000, v195
	v_lshlrev_b32_e32 v209, 16, v196
	v_and_b32_e32 v196, 0xffff0000, v196
	v_lshlrev_b32_e32 v210, 16, v197
	v_and_b32_e32 v197, 0xffff0000, v197
	v_fmac_f32_e32 v190, 0.5, v117
	v_fmac_f32_e32 v191, 0.5, v119
	v_fmac_f32_e32 v192, 0.5, v113
	v_fmac_f32_e32 v193, 0.5, v115
	v_fmac_f32_e32 v194, 0.5, v125
	v_fmac_f32_e32 v195, 0.5, v127
	v_fmac_f32_e32 v196, 0.5, v121
	v_fmac_f32_e32 v197, 0.5, v123
	v_fmac_f32_e32 v203, 0.5, v116
	v_fmac_f32_e32 v204, 0.5, v118
	v_fmac_f32_e32 v205, 0.5, v112
	v_fmac_f32_e32 v206, 0.5, v114
	v_fmac_f32_e32 v207, 0.5, v124
	v_fmac_f32_e32 v208, 0.5, v126
	v_fmac_f32_e32 v209, 0.5, v120
	v_fmac_f32_e32 v210, 0.5, v122
	v_mul_f32_e32 v112, v190, v190
	v_mul_f32_e32 v113, v191, v191
	v_mul_f32_e32 v118, v192, v192
	v_mul_f32_e32 v119, v193, v193
	v_mul_f32_e32 v120, v194, v194
	v_mul_f32_e32 v121, v195, v195
	v_mul_f32_e32 v122, v196, v196
	v_mul_f32_e32 v123, v197, v197
	v_fmac_f32_e32 v112, v203, v203
	v_fmac_f32_e32 v113, v204, v204
	v_fmac_f32_e32 v118, v205, v205
	v_fmac_f32_e32 v119, v206, v206
	v_fmac_f32_e32 v120, v207, v207
	v_fmac_f32_e32 v121, v208, v208
	v_fmac_f32_e32 v122, v209, v209
	v_fmac_f32_e32 v123, v210, v210
	v_add_f32_e32 v112, v112, v113
	v_add_f32_e32 v113, v118, v119
	v_add_f32_e32 v118, v120, v121
	v_add_f32_e32 v119, v122, v123
	v_cndmask_b32_e32 v189, v188, v189, vcc
	v_add_f32_e32 v112, v112, v113
	v_add_f32_e32 v113, v118, v119
	v_add_f32_e32 v113, v112, v113
	v_lshlrev_b32_e32 v112, 2, v189
	ds_bpermute_b32 v122, v112, v113
	v_lshl_add_u64 v[118:119], s[0:1], 0, v[200:201]
	v_cvt_pk_bf16_f32 v114, v203, v190
	v_lshl_add_u64 v[120:121], v[118:119], 0, v[198:199]
	v_cvt_pk_bf16_f32 v115, v204, v191
	v_cvt_pk_bf16_f32 v116, v205, v192
	v_cvt_pk_bf16_f32 v117, v206, v193
	global_store_dwordx4 v[120:121], v[114:117], off
	s_waitcnt lgkmcnt(0)
	s_nop 0
	v_add_f32_e32 v114, v113, v122
	v_xor_b32_e32 v113, 32, v188
	v_cmp_lt_i32_e32 vcc, v113, v202
	v_cvt_pk_bf16_f32 v116, v207, v194
	v_cvt_pk_bf16_f32 v117, v208, v195
	v_cvt_pk_bf16_f32 v118, v209, v196
	v_cvt_pk_bf16_f32 v119, v210, v197
	global_store_dwordx4 v[120:121], v[116:119], off offset:256
	s_nop 0
	v_cndmask_b32_e32 v113, v188, v113, vcc
	v_lshlrev_b32_e32 v113, 2, v113
	ds_bpermute_b32 v115, v113, v114
	s_and_saveexec_b64 s[20:21], s[4:5]
	s_cbranch_execz .LBB0_1909
	s_waitcnt lgkmcnt(0)
	v_add_f32_e32 v116, v114, v115
	s_lshl_b32 s22, s30, 2
	v_lshlrev_b64 v[114:115], 7, v[168:169]
	s_ashr_i32 s23, s22, 31
	v_lshl_add_u64 v[114:115], s[8:9], 0, v[114:115]
	v_lshl_add_u64 v[114:115], s[22:23], 2, v[114:115]
	s_lshl_b32 s2, s41, 2
	v_lshl_add_u64 v[114:115], v[114:115], 0, s[2:3]
	global_store_dword v[114:115], v116, off
